# EpiRes (Wo/Down) epilogue fast paths: base-load pool deepened from 8 to 14 tuples (more loads in flight per wave)
# speedup vs baseline: 1.0033x; 1.0033x over previous
; __device__ __forceinline__ unsigned pkbf(float lo, float hi) { f32x2_t v = {lo, hi}; bf16x2_t b = __builtin_convertvector(v, bf16x2_t); return __builtin_bit_cast(unsigned, b); }
;     __device__ __forceinline__ void operator()(const f32x4 (&acc)[2][2][4][2], const pg8::Unit& u, int wr, int wc, int fr, int fq) const {
;     ...
;         const bool bf = isctx || base_f32, of = isctx || out_f32;
;         const float* bpf = isctx ? base_ctx : (const float*)base_lat; float* opf = isctx ? out_ctx : (float*)out_lat;
;         const bf16_t* bph = (const bf16_t*)base_lat; bf16_t* oph = (bf16_t*)out_lat;
; #pragma unroll
;         for (int ai = 0; ai < 2; ++ai)
; #pragma unroll
;             for (int m = 0; m < 4; ++m) { const size_t off = (size_t)(row0 + ai * 128 + m * 16) * DM + col0;
; #pragma unroll
;                 for (int bj = 0; bj < 2; ++bj) {
;                     f32x4 b0, b1;
;                     if (bf) { b0 = *(const f32x4*)(bpf + off + bj * 128); b1 = *(const f32x4*)(bpf + off + bj * 128 + 4); }
;                     else { const u32x4 w = *(const u32x4*)(bph + off + bj * 128);
;                         b0 = (f32x4){__uint_as_float(w.x << 16), __uint_as_float(w.x & 0xffff0000u), __uint_as_float(w.y << 16), __uint_as_float(w.y & 0xffff0000u)};
;                         b1 = (f32x4){__uint_as_float(w.z << 16), __uint_as_float(w.z & 0xffff0000u), __uint_as_float(w.w << 16), __uint_as_float(w.w & 0xffff0000u)}; }
;                     const f32x4 o0 = b0 + g[bj][0] * acc[ai][bj][m][0], o1 = b1 + g[bj][1] * acc[ai][bj][m][1];
;                     if (of) { *(f32x4*)(opf + off + bj * 128) = o0; *(f32x4*)(opf + off + bj * 128 + 4) = o1; }
;                     else { u32x4 w; w.x = pkbf(o0[0], o0[1]); w.y = pkbf(o0[2], o0[3]); w.z = pkbf(o1[0], o1[1]); w.w = pkbf(o1[2], o1[3]); *(u32x4*)(oph + off + bj * 128) = w; } } }
.LBB0_541:
	s_andn2_b64 vcc, exec, s[10:11]
	s_cbranch_vccnz .LBB0_670
	s_and_b64 vcc, exec, s[0:1]
	s_cbranch_vccnz .Lepi_wo_orig
	v_readlane_b32 s30, v240, 36
	s_nop 0
	s_cmp_eq_u32 s30, 0
	s_cbranch_scc1 .Lepi_wo_bf
	v_lshl_add_u32 v144, v172, 10, v170
	v_lshlrev_b32_e32 v145, 2, v144
	v_lshlrev_b32_e32 v144, 1, v144
	v_readfirstlane_b32 s8, v158
	v_readfirstlane_b32 s9, v159
	s_mov_b32 s10, s70
	s_mov_b32 s11, s71
	s_nop 4
	global_load_dwordx4 v[198:201], v145, s[8:9]
	global_load_dwordx4 v[202:205], v145, s[8:9] offset:16
	global_load_dwordx4 v[206:209], v145, s[8:9] offset:512
	global_load_dwordx4 v[210:213], v145, s[8:9] offset:528
	s_add_u32 s8, s8, 0x10000
	s_addc_u32 s9, s9, 0
	global_load_dwordx4 v[214:217], v145, s[8:9]
	global_load_dwordx4 v[218:221], v145, s[8:9] offset:16
	global_load_dwordx4 v[222:225], v145, s[8:9] offset:512
	global_load_dwordx4 v[188:191], v145, s[8:9] offset:528
	s_add_u32 s8, s8, 0x10000
	s_addc_u32 s9, s9, 0
	global_load_dwordx4 v[226:229], v145, s[8:9]
	global_load_dwordx4 v[230:233], v145, s[8:9] offset:16
	global_load_dwordx4 v[234:237], v145, s[8:9] offset:512
	global_load_dwordx4 v[244:247], v145, s[8:9] offset:528
	s_add_u32 s8, s8, 0x10000
	s_addc_u32 s9, s9, 0
	global_load_dwordx4 v[248:251], v145, s[8:9]
	global_load_dwordx4 v[252:255], v145, s[8:9] offset:16
	s_waitcnt vmcnt(12)
	v_pk_fma_f32 v[140:141], v[140:141], v[112:113], v[198:199]
	v_pk_fma_f32 v[142:143], v[142:143], v[114:115], v[200:201]
	v_pk_fma_f32 v[136:137], v[136:137], v[104:105], v[202:203]
	v_pk_fma_f32 v[138:139], v[138:139], v[106:107], v[204:205]
	global_load_dwordx4 v[198:201], v145, s[8:9] offset:512
	global_load_dwordx4 v[202:205], v145, s[8:9] offset:528
	v_cvt_pk_bf16_f32 v140, v140, v141
	v_cvt_pk_bf16_f32 v141, v142, v143
	v_cvt_pk_bf16_f32 v142, v136, v137
	v_cvt_pk_bf16_f32 v143, v138, v139
	global_store_dwordx4 v144, v[140:143], s[10:11]
	s_waitcnt vmcnt(13)
	v_pk_fma_f32 v[132:133], v[132:133], v[100:101], v[206:207]
	v_pk_fma_f32 v[134:135], v[134:135], v[102:103], v[208:209]
	v_pk_fma_f32 v[128:129], v[128:129], v[92:93], v[210:211]
	v_pk_fma_f32 v[130:131], v[130:131], v[94:95], v[212:213]
	s_add_u32 s8, s8, 0x50000
	s_addc_u32 s9, s9, 0
	global_load_dwordx4 v[206:209], v145, s[8:9]
	global_load_dwordx4 v[210:213], v145, s[8:9] offset:16
	v_cvt_pk_bf16_f32 v132, v132, v133
	v_cvt_pk_bf16_f32 v133, v134, v135
	v_cvt_pk_bf16_f32 v134, v128, v129
	v_cvt_pk_bf16_f32 v135, v130, v131
	global_store_dwordx4 v144, v[132:135], s[10:11] offset:256
	s_waitcnt vmcnt(14)
	v_pk_fma_f32 v[124:125], v[124:125], v[112:113], v[214:215]
	v_pk_fma_f32 v[126:127], v[126:127], v[114:115], v[216:217]
	v_pk_fma_f32 v[120:121], v[120:121], v[104:105], v[218:219]
	v_pk_fma_f32 v[122:123], v[122:123], v[106:107], v[220:221]
	global_load_dwordx4 v[214:217], v145, s[8:9] offset:512
	global_load_dwordx4 v[218:221], v145, s[8:9] offset:528
	s_add_u32 s10, s10, 0x8000
	s_addc_u32 s11, s11, 0
	v_cvt_pk_bf16_f32 v124, v124, v125
	v_cvt_pk_bf16_f32 v125, v126, v127
	v_cvt_pk_bf16_f32 v126, v120, v121
	v_cvt_pk_bf16_f32 v127, v122, v123
	global_store_dwordx4 v144, v[124:127], s[10:11]
	s_waitcnt vmcnt(15)
	v_pk_fma_f32 v[116:117], v[116:117], v[100:101], v[222:223]
	v_pk_fma_f32 v[118:119], v[118:119], v[102:103], v[224:225]
	v_pk_fma_f32 v[108:109], v[108:109], v[92:93], v[188:189]
	v_pk_fma_f32 v[110:111], v[110:111], v[94:95], v[190:191]
	s_add_u32 s8, s8, 0x10000
	s_addc_u32 s9, s9, 0
	global_load_dwordx4 v[222:225], v145, s[8:9]
	global_load_dwordx4 v[188:191], v145, s[8:9] offset:16
	v_cvt_pk_bf16_f32 v116, v116, v117
	v_cvt_pk_bf16_f32 v117, v118, v119
	v_cvt_pk_bf16_f32 v118, v108, v109
	v_cvt_pk_bf16_f32 v119, v110, v111
	global_store_dwordx4 v144, v[116:119], s[10:11] offset:256
	s_waitcnt vmcnt(16)
	v_pk_fma_f32 v[96:97], v[96:97], v[112:113], v[226:227]
	v_pk_fma_f32 v[98:99], v[98:99], v[114:115], v[228:229]
	v_pk_fma_f32 v[88:89], v[88:89], v[104:105], v[230:231]
	v_pk_fma_f32 v[90:91], v[90:91], v[106:107], v[232:233]
	global_load_dwordx4 v[226:229], v145, s[8:9] offset:512
	global_load_dwordx4 v[230:233], v145, s[8:9] offset:528
	s_add_u32 s10, s10, 0x8000
	s_addc_u32 s11, s11, 0
	v_cvt_pk_bf16_f32 v96, v96, v97
	v_cvt_pk_bf16_f32 v97, v98, v99
	v_cvt_pk_bf16_f32 v98, v88, v89
	v_cvt_pk_bf16_f32 v99, v90, v91
	global_store_dwordx4 v144, v[96:99], s[10:11]
	s_waitcnt vmcnt(17)
	v_pk_fma_f32 v[84:85], v[84:85], v[100:101], v[234:235]
	v_pk_fma_f32 v[86:87], v[86:87], v[102:103], v[236:237]
	v_pk_fma_f32 v[80:81], v[80:81], v[92:93], v[244:245]
	v_pk_fma_f32 v[82:83], v[82:83], v[94:95], v[246:247]
	s_add_u32 s8, s8, 0x10000
	s_addc_u32 s9, s9, 0
	global_load_dwordx4 v[234:237], v145, s[8:9]
	global_load_dwordx4 v[244:247], v145, s[8:9] offset:16
	v_cvt_pk_bf16_f32 v84, v84, v85
	v_cvt_pk_bf16_f32 v85, v86, v87
	v_cvt_pk_bf16_f32 v86, v80, v81
	v_cvt_pk_bf16_f32 v87, v82, v83
	global_store_dwordx4 v144, v[84:87], s[10:11] offset:256
	s_waitcnt vmcnt(18)
	v_pk_fma_f32 v[76:77], v[76:77], v[112:113], v[248:249]
	v_pk_fma_f32 v[78:79], v[78:79], v[114:115], v[250:251]
	v_pk_fma_f32 v[72:73], v[72:73], v[104:105], v[252:253]
	v_pk_fma_f32 v[74:75], v[74:75], v[106:107], v[254:255]
	global_load_dwordx4 v[248:251], v145, s[8:9] offset:512
	global_load_dwordx4 v[252:255], v145, s[8:9] offset:528
	s_add_u32 s10, s10, 0x8000
	s_addc_u32 s11, s11, 0
	v_cvt_pk_bf16_f32 v76, v76, v77
	v_cvt_pk_bf16_f32 v77, v78, v79
	v_cvt_pk_bf16_f32 v78, v72, v73
	v_cvt_pk_bf16_f32 v79, v74, v75
	global_store_dwordx4 v144, v[76:79], s[10:11]
	s_waitcnt vmcnt(19)
; __device__ __forceinline__ unsigned pkbf(float lo, float hi) { f32x2_t v = {lo, hi}; bf16x2_t b = __builtin_convertvector(v, bf16x2_t); return __builtin_bit_cast(unsigned, b); }
;     __device__ __forceinline__ void operator()(const f32x4 (&acc)[2][2][4][2], const pg8::Unit& u, int wr, int wc, int fr, int fq) const {
;     ...
;         const bool bf = isctx || base_f32, of = isctx || out_f32;
;         const float* bpf = isctx ? base_ctx : (const float*)base_lat; float* opf = isctx ? out_ctx : (float*)out_lat;
;         const bf16_t* bph = (const bf16_t*)base_lat; bf16_t* oph = (bf16_t*)out_lat;
; #pragma unroll
;         for (int ai = 0; ai < 2; ++ai)
; #pragma unroll
;             for (int m = 0; m < 4; ++m) { const size_t off = (size_t)(row0 + ai * 128 + m * 16) * DM + col0;
; #pragma unroll
;                 for (int bj = 0; bj < 2; ++bj) {
;                     f32x4 b0, b1;
;                     if (bf) { b0 = *(const f32x4*)(bpf + off + bj * 128); b1 = *(const f32x4*)(bpf + off + bj * 128 + 4); }
;                     else { const u32x4 w = *(const u32x4*)(bph + off + bj * 128);
;                         b0 = (f32x4){__uint_as_float(w.x << 16), __uint_as_float(w.x & 0xffff0000u), __uint_as_float(w.y << 16), __uint_as_float(w.y & 0xffff0000u)};
;                         b1 = (f32x4){__uint_as_float(w.z << 16), __uint_as_float(w.z & 0xffff0000u), __uint_as_float(w.w << 16), __uint_as_float(w.w & 0xffff0000u)}; }
;                     const f32x4 o0 = b0 + g[bj][0] * acc[ai][bj][m][0], o1 = b1 + g[bj][1] * acc[ai][bj][m][1];
;                     if (of) { *(f32x4*)(opf + off + bj * 128) = o0; *(f32x4*)(opf + off + bj * 128 + 4) = o1; }
;                     else { u32x4 w; w.x = pkbf(o0[0], o0[1]); w.y = pkbf(o0[2], o0[3]); w.z = pkbf(o1[0], o1[1]); w.w = pkbf(o1[2], o1[3]); *(u32x4*)(oph + off + bj * 128) = w; } } }
	v_pk_fma_f32 v[68:69], v[68:69], v[100:101], v[198:199]
	v_pk_fma_f32 v[70:71], v[70:71], v[102:103], v[200:201]
	v_pk_fma_f32 v[64:65], v[64:65], v[92:93], v[202:203]
	v_pk_fma_f32 v[66:67], v[66:67], v[94:95], v[204:205]
	s_add_u32 s8, s8, 0x10000
	s_addc_u32 s9, s9, 0
	global_load_dwordx4 v[198:201], v145, s[8:9]
	global_load_dwordx4 v[202:205], v145, s[8:9] offset:16
	v_cvt_pk_bf16_f32 v68, v68, v69
	v_cvt_pk_bf16_f32 v69, v70, v71
	v_cvt_pk_bf16_f32 v70, v64, v65
	v_cvt_pk_bf16_f32 v71, v66, v67
	global_store_dwordx4 v144, v[68:71], s[10:11] offset:256
	s_waitcnt vmcnt(19)
	v_pk_fma_f32 v[60:61], v[60:61], v[112:113], v[206:207]
	v_pk_fma_f32 v[62:63], v[62:63], v[114:115], v[208:209]
	v_pk_fma_f32 v[56:57], v[56:57], v[104:105], v[210:211]
	v_pk_fma_f32 v[58:59], v[58:59], v[106:107], v[212:213]
	global_load_dwordx4 v[206:209], v145, s[8:9] offset:512
	global_load_dwordx4 v[210:213], v145, s[8:9] offset:528
	s_add_u32 s10, s10, 0x28000
	s_addc_u32 s11, s11, 0
	v_cvt_pk_bf16_f32 v60, v60, v61
	v_cvt_pk_bf16_f32 v61, v62, v63
	v_cvt_pk_bf16_f32 v62, v56, v57
	v_cvt_pk_bf16_f32 v63, v58, v59
	global_store_dwordx4 v144, v[60:63], s[10:11]
	s_waitcnt vmcnt(19)
	v_pk_fma_f32 v[52:53], v[52:53], v[100:101], v[214:215]
	v_pk_fma_f32 v[54:55], v[54:55], v[102:103], v[216:217]
	v_pk_fma_f32 v[48:49], v[48:49], v[92:93], v[218:219]
	v_pk_fma_f32 v[50:51], v[50:51], v[94:95], v[220:221]
	v_cvt_pk_bf16_f32 v52, v52, v53
	v_cvt_pk_bf16_f32 v53, v54, v55
	v_cvt_pk_bf16_f32 v54, v48, v49
	v_cvt_pk_bf16_f32 v55, v50, v51
	global_store_dwordx4 v144, v[52:55], s[10:11] offset:256
	s_waitcnt vmcnt(17)
	v_pk_fma_f32 v[44:45], v[44:45], v[112:113], v[222:223]
	v_pk_fma_f32 v[46:47], v[46:47], v[114:115], v[224:225]
	v_pk_fma_f32 v[40:41], v[40:41], v[104:105], v[188:189]
	v_pk_fma_f32 v[42:43], v[42:43], v[106:107], v[190:191]
	s_add_u32 s10, s10, 0x8000
	s_addc_u32 s11, s11, 0
	v_cvt_pk_bf16_f32 v44, v44, v45
	v_cvt_pk_bf16_f32 v45, v46, v47
	v_cvt_pk_bf16_f32 v46, v40, v41
	v_cvt_pk_bf16_f32 v47, v42, v43
	global_store_dwordx4 v144, v[44:47], s[10:11]
	s_waitcnt vmcnt(15)
	v_pk_fma_f32 v[36:37], v[36:37], v[100:101], v[226:227]
	v_pk_fma_f32 v[38:39], v[38:39], v[102:103], v[228:229]
	v_pk_fma_f32 v[32:33], v[32:33], v[92:93], v[230:231]
	v_pk_fma_f32 v[34:35], v[34:35], v[94:95], v[232:233]
	v_cvt_pk_bf16_f32 v36, v36, v37
	v_cvt_pk_bf16_f32 v37, v38, v39
	v_cvt_pk_bf16_f32 v38, v32, v33
	v_cvt_pk_bf16_f32 v39, v34, v35
	global_store_dwordx4 v144, v[36:39], s[10:11] offset:256
	s_waitcnt vmcnt(13)
	v_pk_fma_f32 v[28:29], v[28:29], v[112:113], v[234:235]
	v_pk_fma_f32 v[30:31], v[30:31], v[114:115], v[236:237]
	v_pk_fma_f32 v[24:25], v[24:25], v[104:105], v[244:245]
	v_pk_fma_f32 v[26:27], v[26:27], v[106:107], v[246:247]
	s_add_u32 s10, s10, 0x8000
	s_addc_u32 s11, s11, 0
	v_cvt_pk_bf16_f32 v28, v28, v29
	v_cvt_pk_bf16_f32 v29, v30, v31
	v_cvt_pk_bf16_f32 v30, v24, v25
	v_cvt_pk_bf16_f32 v31, v26, v27
	global_store_dwordx4 v144, v[28:31], s[10:11]
	s_waitcnt vmcnt(11)
	v_pk_fma_f32 v[20:21], v[20:21], v[100:101], v[248:249]
	v_pk_fma_f32 v[22:23], v[22:23], v[102:103], v[250:251]
	v_pk_fma_f32 v[16:17], v[16:17], v[92:93], v[252:253]
	v_pk_fma_f32 v[18:19], v[18:19], v[94:95], v[254:255]
	v_cvt_pk_bf16_f32 v20, v20, v21
	v_cvt_pk_bf16_f32 v21, v22, v23
	v_cvt_pk_bf16_f32 v22, v16, v17
	v_cvt_pk_bf16_f32 v23, v18, v19
	global_store_dwordx4 v144, v[20:23], s[10:11] offset:256
	s_waitcnt vmcnt(9)
	v_pk_fma_f32 v[12:13], v[12:13], v[112:113], v[198:199]
	v_pk_fma_f32 v[14:15], v[14:15], v[114:115], v[200:201]
	v_pk_fma_f32 v[8:9], v[8:9], v[104:105], v[202:203]
	v_pk_fma_f32 v[10:11], v[10:11], v[106:107], v[204:205]
	s_add_u32 s10, s10, 0x8000
	s_addc_u32 s11, s11, 0
	v_cvt_pk_bf16_f32 v12, v12, v13
	v_cvt_pk_bf16_f32 v13, v14, v15
	v_cvt_pk_bf16_f32 v14, v8, v9
	v_cvt_pk_bf16_f32 v15, v10, v11
	global_store_dwordx4 v144, v[12:15], s[10:11]
	s_waitcnt vmcnt(7)
	v_pk_fma_f32 v[4:5], v[4:5], v[100:101], v[206:207]
	v_pk_fma_f32 v[6:7], v[6:7], v[102:103], v[208:209]
	v_pk_fma_f32 v[0:1], v[0:1], v[92:93], v[210:211]
	v_pk_fma_f32 v[2:3], v[2:3], v[94:95], v[212:213]
	v_cvt_pk_bf16_f32 v4, v4, v5
	v_cvt_pk_bf16_f32 v5, v6, v7
	v_cvt_pk_bf16_f32 v6, v0, v1
	v_cvt_pk_bf16_f32 v7, v2, v3
	global_store_dwordx4 v144, v[4:7], s[10:11] offset:256
	s_branch .LBB0_670
; __device__ __forceinline__ unsigned pkbf(float lo, float hi) { f32x2_t v = {lo, hi}; bf16x2_t b = __builtin_convertvector(v, bf16x2_t); return __builtin_bit_cast(unsigned, b); }
;     __device__ __forceinline__ void operator()(const f32x4 (&acc)[2][2][4][2], const pg8::Unit& u, int wr, int wc, int fr, int fq) const {
;     ...
;         const bool bf = isctx || base_f32, of = isctx || out_f32;
;         const float* bpf = isctx ? base_ctx : (const float*)base_lat; float* opf = isctx ? out_ctx : (float*)out_lat;
;         const bf16_t* bph = (const bf16_t*)base_lat; bf16_t* oph = (bf16_t*)out_lat;
; #pragma unroll
;         for (int ai = 0; ai < 2; ++ai)
; #pragma unroll
;             for (int m = 0; m < 4; ++m) { const size_t off = (size_t)(row0 + ai * 128 + m * 16) * DM + col0;
; #pragma unroll
;                 for (int bj = 0; bj < 2; ++bj) {
;                     f32x4 b0, b1;
;                     if (bf) { b0 = *(const f32x4*)(bpf + off + bj * 128); b1 = *(const f32x4*)(bpf + off + bj * 128 + 4); }
;                     else { const u32x4 w = *(const u32x4*)(bph + off + bj * 128);
;                         b0 = (f32x4){__uint_as_float(w.x << 16), __uint_as_float(w.x & 0xffff0000u), __uint_as_float(w.y << 16), __uint_as_float(w.y & 0xffff0000u)};
;                         b1 = (f32x4){__uint_as_float(w.z << 16), __uint_as_float(w.z & 0xffff0000u), __uint_as_float(w.w << 16), __uint_as_float(w.w & 0xffff0000u)}; }
;                     const f32x4 o0 = b0 + g[bj][0] * acc[ai][bj][m][0], o1 = b1 + g[bj][1] * acc[ai][bj][m][1];
;                     if (of) { *(f32x4*)(opf + off + bj * 128) = o0; *(f32x4*)(opf + off + bj * 128 + 4) = o1; }
;                     else { u32x4 w; w.x = pkbf(o0[0], o0[1]); w.y = pkbf(o0[2], o0[3]); w.z = pkbf(o1[0], o1[1]); w.w = pkbf(o1[2], o1[3]); *(u32x4*)(oph + off + bj * 128) = w; } } }
.Lepi_wo_bf:
	v_lshl_add_u32 v144, v172, 10, v170
	v_lshlrev_b32_e32 v145, 2, v144
	v_lshlrev_b32_e32 v144, 1, v144
	v_readfirstlane_b32 s8, v158
	v_readfirstlane_b32 s9, v159
	s_mov_b32 s10, s70
	s_mov_b32 s11, s71
	s_nop 4
	global_load_dwordx4 v[198:201], v144, s[8:9]
	global_load_dwordx4 v[202:205], v144, s[8:9] offset:256
	s_add_u32 s8, s8, 0x8000
	s_addc_u32 s9, s9, 0
	global_load_dwordx4 v[206:209], v144, s[8:9]
	global_load_dwordx4 v[210:213], v144, s[8:9] offset:256
	s_add_u32 s8, s8, 0x8000
	s_addc_u32 s9, s9, 0
	global_load_dwordx4 v[214:217], v144, s[8:9]
	global_load_dwordx4 v[218:221], v144, s[8:9] offset:256
	s_add_u32 s8, s8, 0x8000
	s_addc_u32 s9, s9, 0
	global_load_dwordx4 v[222:225], v144, s[8:9]
	global_load_dwordx4 v[188:191], v144, s[8:9] offset:256
	s_add_u32 s8, s8, 0x28000
	s_addc_u32 s9, s9, 0
	global_load_dwordx4 v[226:229], v144, s[8:9]
	global_load_dwordx4 v[230:233], v144, s[8:9] offset:256
	s_add_u32 s8, s8, 0x8000
	s_addc_u32 s9, s9, 0
	global_load_dwordx4 v[234:237], v144, s[8:9]
	global_load_dwordx4 v[244:247], v144, s[8:9] offset:256
	s_add_u32 s8, s8, 0x8000
	s_addc_u32 s9, s9, 0
	global_load_dwordx4 v[248:251], v144, s[8:9]
	global_load_dwordx4 v[252:255], v144, s[8:9] offset:256
	s_waitcnt vmcnt(13)
	v_lshlrev_b32_e32 v176, 16, v198
	v_and_b32_e32 v177, 0xffff0000, v198
	v_lshlrev_b32_e32 v178, 16, v199
	v_and_b32_e32 v179, 0xffff0000, v199
	v_lshlrev_b32_e32 v180, 16, v200
	v_and_b32_e32 v181, 0xffff0000, v200
	v_lshlrev_b32_e32 v182, 16, v201
	v_and_b32_e32 v183, 0xffff0000, v201
	v_pk_fma_f32 v[140:141], v[140:141], v[112:113], v[176:177]
	v_pk_fma_f32 v[142:143], v[142:143], v[114:115], v[178:179]
	v_pk_fma_f32 v[136:137], v[136:137], v[104:105], v[180:181]
	v_pk_fma_f32 v[138:139], v[138:139], v[106:107], v[182:183]
	s_add_u32 s8, s8, 0x8000
	s_addc_u32 s9, s9, 0
	global_load_dwordx4 v[198:201], v144, s[8:9]
	v_cvt_pk_bf16_f32 v140, v140, v141
	v_cvt_pk_bf16_f32 v141, v142, v143
	v_cvt_pk_bf16_f32 v142, v136, v137
	v_cvt_pk_bf16_f32 v143, v138, v139
	global_store_dwordx4 v144, v[140:143], s[10:11]
	s_waitcnt vmcnt(14)
	v_lshlrev_b32_e32 v176, 16, v202
	v_and_b32_e32 v177, 0xffff0000, v202
	v_lshlrev_b32_e32 v178, 16, v203
	v_and_b32_e32 v179, 0xffff0000, v203
	v_lshlrev_b32_e32 v180, 16, v204
	v_and_b32_e32 v181, 0xffff0000, v204
	v_lshlrev_b32_e32 v182, 16, v205
	v_and_b32_e32 v183, 0xffff0000, v205
	v_pk_fma_f32 v[132:133], v[132:133], v[100:101], v[176:177]
	v_pk_fma_f32 v[134:135], v[134:135], v[102:103], v[178:179]
	v_pk_fma_f32 v[128:129], v[128:129], v[92:93], v[180:181]
	v_pk_fma_f32 v[130:131], v[130:131], v[94:95], v[182:183]
	global_load_dwordx4 v[202:205], v144, s[8:9] offset:256
	v_cvt_pk_bf16_f32 v132, v132, v133
	v_cvt_pk_bf16_f32 v133, v134, v135
	v_cvt_pk_bf16_f32 v134, v128, v129
	v_cvt_pk_bf16_f32 v135, v130, v131
	global_store_dwordx4 v144, v[132:135], s[10:11] offset:256
	s_waitcnt vmcnt(15)
	v_lshlrev_b32_e32 v176, 16, v206
	v_and_b32_e32 v177, 0xffff0000, v206
	v_lshlrev_b32_e32 v178, 16, v207
	v_and_b32_e32 v179, 0xffff0000, v207
	v_lshlrev_b32_e32 v180, 16, v208
	v_and_b32_e32 v181, 0xffff0000, v208
	v_lshlrev_b32_e32 v182, 16, v209
	v_and_b32_e32 v183, 0xffff0000, v209
	v_pk_fma_f32 v[124:125], v[124:125], v[112:113], v[176:177]
	v_pk_fma_f32 v[126:127], v[126:127], v[114:115], v[178:179]
	v_pk_fma_f32 v[120:121], v[120:121], v[104:105], v[180:181]
	v_pk_fma_f32 v[122:123], v[122:123], v[106:107], v[182:183]
	s_add_u32 s10, s10, 0x8000
	s_addc_u32 s11, s11, 0
	v_cvt_pk_bf16_f32 v124, v124, v125
	v_cvt_pk_bf16_f32 v125, v126, v127
	v_cvt_pk_bf16_f32 v126, v120, v121
	v_cvt_pk_bf16_f32 v127, v122, v123
	global_store_dwordx4 v144, v[124:127], s[10:11]
	s_waitcnt vmcnt(15)
	v_lshlrev_b32_e32 v176, 16, v210
	v_and_b32_e32 v177, 0xffff0000, v210
	v_lshlrev_b32_e32 v178, 16, v211
	v_and_b32_e32 v179, 0xffff0000, v211
	v_lshlrev_b32_e32 v180, 16, v212
	v_and_b32_e32 v181, 0xffff0000, v212
	v_lshlrev_b32_e32 v182, 16, v213
	v_and_b32_e32 v183, 0xffff0000, v213
	v_pk_fma_f32 v[116:117], v[116:117], v[100:101], v[176:177]
	v_pk_fma_f32 v[118:119], v[118:119], v[102:103], v[178:179]
	v_pk_fma_f32 v[108:109], v[108:109], v[92:93], v[180:181]
	v_pk_fma_f32 v[110:111], v[110:111], v[94:95], v[182:183]
	v_cvt_pk_bf16_f32 v116, v116, v117
	v_cvt_pk_bf16_f32 v117, v118, v119
	v_cvt_pk_bf16_f32 v118, v108, v109
	v_cvt_pk_bf16_f32 v119, v110, v111
	global_store_dwordx4 v144, v[116:119], s[10:11] offset:256
	s_waitcnt vmcnt(15)
	v_lshlrev_b32_e32 v176, 16, v214
	v_and_b32_e32 v177, 0xffff0000, v214
	v_lshlrev_b32_e32 v178, 16, v215
	v_and_b32_e32 v179, 0xffff0000, v215
	v_lshlrev_b32_e32 v180, 16, v216
	v_and_b32_e32 v181, 0xffff0000, v216
	v_lshlrev_b32_e32 v182, 16, v217
	v_and_b32_e32 v183, 0xffff0000, v217
	v_pk_fma_f32 v[96:97], v[96:97], v[112:113], v[176:177]
	v_pk_fma_f32 v[98:99], v[98:99], v[114:115], v[178:179]
	v_pk_fma_f32 v[88:89], v[88:89], v[104:105], v[180:181]
	v_pk_fma_f32 v[90:91], v[90:91], v[106:107], v[182:183]
	s_add_u32 s10, s10, 0x8000
	s_addc_u32 s11, s11, 0
	v_cvt_pk_bf16_f32 v96, v96, v97
	v_cvt_pk_bf16_f32 v97, v98, v99
	v_cvt_pk_bf16_f32 v98, v88, v89
	v_cvt_pk_bf16_f32 v99, v90, v91
	global_store_dwordx4 v144, v[96:99], s[10:11]
	s_waitcnt vmcnt(15)
	v_lshlrev_b32_e32 v176, 16, v218
	v_and_b32_e32 v177, 0xffff0000, v218
	v_lshlrev_b32_e32 v178, 16, v219
	v_and_b32_e32 v179, 0xffff0000, v219
	v_lshlrev_b32_e32 v180, 16, v220
	v_and_b32_e32 v181, 0xffff0000, v220
	v_lshlrev_b32_e32 v182, 16, v221
	v_and_b32_e32 v183, 0xffff0000, v221
	v_pk_fma_f32 v[84:85], v[84:85], v[100:101], v[176:177]
	v_pk_fma_f32 v[86:87], v[86:87], v[102:103], v[178:179]
	v_pk_fma_f32 v[80:81], v[80:81], v[92:93], v[180:181]
	v_pk_fma_f32 v[82:83], v[82:83], v[94:95], v[182:183]
	v_cvt_pk_bf16_f32 v84, v84, v85
	v_cvt_pk_bf16_f32 v85, v86, v87
	v_cvt_pk_bf16_f32 v86, v80, v81
	v_cvt_pk_bf16_f32 v87, v82, v83
	global_store_dwordx4 v144, v[84:87], s[10:11] offset:256
	s_waitcnt vmcnt(15)
; __device__ __forceinline__ unsigned pkbf(float lo, float hi) { f32x2_t v = {lo, hi}; bf16x2_t b = __builtin_convertvector(v, bf16x2_t); return __builtin_bit_cast(unsigned, b); }
;     __device__ __forceinline__ void operator()(const f32x4 (&acc)[2][2][4][2], const pg8::Unit& u, int wr, int wc, int fr, int fq) const {
;     ...
;         const bool bf = isctx || base_f32, of = isctx || out_f32;
;         const float* bpf = isctx ? base_ctx : (const float*)base_lat; float* opf = isctx ? out_ctx : (float*)out_lat;
;         const bf16_t* bph = (const bf16_t*)base_lat; bf16_t* oph = (bf16_t*)out_lat;
; #pragma unroll
;         for (int ai = 0; ai < 2; ++ai)
; #pragma unroll
;             for (int m = 0; m < 4; ++m) { const size_t off = (size_t)(row0 + ai * 128 + m * 16) * DM + col0;
; #pragma unroll
;                 for (int bj = 0; bj < 2; ++bj) {
;                     f32x4 b0, b1;
;                     if (bf) { b0 = *(const f32x4*)(bpf + off + bj * 128); b1 = *(const f32x4*)(bpf + off + bj * 128 + 4); }
;                     else { const u32x4 w = *(const u32x4*)(bph + off + bj * 128);
;                         b0 = (f32x4){__uint_as_float(w.x << 16), __uint_as_float(w.x & 0xffff0000u), __uint_as_float(w.y << 16), __uint_as_float(w.y & 0xffff0000u)};
;                         b1 = (f32x4){__uint_as_float(w.z << 16), __uint_as_float(w.z & 0xffff0000u), __uint_as_float(w.w << 16), __uint_as_float(w.w & 0xffff0000u)}; }
;                     const f32x4 o0 = b0 + g[bj][0] * acc[ai][bj][m][0], o1 = b1 + g[bj][1] * acc[ai][bj][m][1];
;                     if (of) { *(f32x4*)(opf + off + bj * 128) = o0; *(f32x4*)(opf + off + bj * 128 + 4) = o1; }
;                     else { u32x4 w; w.x = pkbf(o0[0], o0[1]); w.y = pkbf(o0[2], o0[3]); w.z = pkbf(o1[0], o1[1]); w.w = pkbf(o1[2], o1[3]); *(u32x4*)(oph + off + bj * 128) = w; } } }
	v_lshlrev_b32_e32 v176, 16, v222
	v_and_b32_e32 v177, 0xffff0000, v222
	v_lshlrev_b32_e32 v178, 16, v223
	v_and_b32_e32 v179, 0xffff0000, v223
	v_lshlrev_b32_e32 v180, 16, v224
	v_and_b32_e32 v181, 0xffff0000, v224
	v_lshlrev_b32_e32 v182, 16, v225
	v_and_b32_e32 v183, 0xffff0000, v225
	v_pk_fma_f32 v[76:77], v[76:77], v[112:113], v[176:177]
	v_pk_fma_f32 v[78:79], v[78:79], v[114:115], v[178:179]
	v_pk_fma_f32 v[72:73], v[72:73], v[104:105], v[180:181]
	v_pk_fma_f32 v[74:75], v[74:75], v[106:107], v[182:183]
	s_add_u32 s10, s10, 0x8000
	s_addc_u32 s11, s11, 0
	v_cvt_pk_bf16_f32 v76, v76, v77
	v_cvt_pk_bf16_f32 v77, v78, v79
	v_cvt_pk_bf16_f32 v78, v72, v73
	v_cvt_pk_bf16_f32 v79, v74, v75
	global_store_dwordx4 v144, v[76:79], s[10:11]
	s_waitcnt vmcnt(15)
	v_lshlrev_b32_e32 v176, 16, v188
	v_and_b32_e32 v177, 0xffff0000, v188
	v_lshlrev_b32_e32 v178, 16, v189
	v_and_b32_e32 v179, 0xffff0000, v189
	v_lshlrev_b32_e32 v180, 16, v190
	v_and_b32_e32 v181, 0xffff0000, v190
	v_lshlrev_b32_e32 v182, 16, v191
	v_and_b32_e32 v183, 0xffff0000, v191
	v_pk_fma_f32 v[68:69], v[68:69], v[100:101], v[176:177]
	v_pk_fma_f32 v[70:71], v[70:71], v[102:103], v[178:179]
	v_pk_fma_f32 v[64:65], v[64:65], v[92:93], v[180:181]
	v_pk_fma_f32 v[66:67], v[66:67], v[94:95], v[182:183]
	v_cvt_pk_bf16_f32 v68, v68, v69
	v_cvt_pk_bf16_f32 v69, v70, v71
	v_cvt_pk_bf16_f32 v70, v64, v65
	v_cvt_pk_bf16_f32 v71, v66, v67
	global_store_dwordx4 v144, v[68:71], s[10:11] offset:256
	s_waitcnt vmcnt(15)
	v_lshlrev_b32_e32 v176, 16, v226
	v_and_b32_e32 v177, 0xffff0000, v226
	v_lshlrev_b32_e32 v178, 16, v227
	v_and_b32_e32 v179, 0xffff0000, v227
	v_lshlrev_b32_e32 v180, 16, v228
	v_and_b32_e32 v181, 0xffff0000, v228
	v_lshlrev_b32_e32 v182, 16, v229
	v_and_b32_e32 v183, 0xffff0000, v229
	v_pk_fma_f32 v[60:61], v[60:61], v[112:113], v[176:177]
	v_pk_fma_f32 v[62:63], v[62:63], v[114:115], v[178:179]
	v_pk_fma_f32 v[56:57], v[56:57], v[104:105], v[180:181]
	v_pk_fma_f32 v[58:59], v[58:59], v[106:107], v[182:183]
	s_add_u32 s10, s10, 0x28000
	s_addc_u32 s11, s11, 0
	v_cvt_pk_bf16_f32 v60, v60, v61
	v_cvt_pk_bf16_f32 v61, v62, v63
	v_cvt_pk_bf16_f32 v62, v56, v57
	v_cvt_pk_bf16_f32 v63, v58, v59
	global_store_dwordx4 v144, v[60:63], s[10:11]
	s_waitcnt vmcnt(15)
	v_lshlrev_b32_e32 v176, 16, v230
	v_and_b32_e32 v177, 0xffff0000, v230
	v_lshlrev_b32_e32 v178, 16, v231
	v_and_b32_e32 v179, 0xffff0000, v231
	v_lshlrev_b32_e32 v180, 16, v232
	v_and_b32_e32 v181, 0xffff0000, v232
	v_lshlrev_b32_e32 v182, 16, v233
	v_and_b32_e32 v183, 0xffff0000, v233
	v_pk_fma_f32 v[52:53], v[52:53], v[100:101], v[176:177]
	v_pk_fma_f32 v[54:55], v[54:55], v[102:103], v[178:179]
	v_pk_fma_f32 v[48:49], v[48:49], v[92:93], v[180:181]
	v_pk_fma_f32 v[50:51], v[50:51], v[94:95], v[182:183]
	v_cvt_pk_bf16_f32 v52, v52, v53
	v_cvt_pk_bf16_f32 v53, v54, v55
	v_cvt_pk_bf16_f32 v54, v48, v49
	v_cvt_pk_bf16_f32 v55, v50, v51
	global_store_dwordx4 v144, v[52:55], s[10:11] offset:256
	s_waitcnt vmcnt(15)
	v_lshlrev_b32_e32 v176, 16, v234
	v_and_b32_e32 v177, 0xffff0000, v234
	v_lshlrev_b32_e32 v178, 16, v235
	v_and_b32_e32 v179, 0xffff0000, v235
	v_lshlrev_b32_e32 v180, 16, v236
	v_and_b32_e32 v181, 0xffff0000, v236
	v_lshlrev_b32_e32 v182, 16, v237
	v_and_b32_e32 v183, 0xffff0000, v237
	v_pk_fma_f32 v[44:45], v[44:45], v[112:113], v[176:177]
	v_pk_fma_f32 v[46:47], v[46:47], v[114:115], v[178:179]
	v_pk_fma_f32 v[40:41], v[40:41], v[104:105], v[180:181]
	v_pk_fma_f32 v[42:43], v[42:43], v[106:107], v[182:183]
	s_add_u32 s10, s10, 0x8000
	s_addc_u32 s11, s11, 0
	v_cvt_pk_bf16_f32 v44, v44, v45
	v_cvt_pk_bf16_f32 v45, v46, v47
	v_cvt_pk_bf16_f32 v46, v40, v41
	v_cvt_pk_bf16_f32 v47, v42, v43
	global_store_dwordx4 v144, v[44:47], s[10:11]
	s_waitcnt vmcnt(15)
; __device__ __forceinline__ unsigned pkbf(float lo, float hi) { f32x2_t v = {lo, hi}; bf16x2_t b = __builtin_convertvector(v, bf16x2_t); return __builtin_bit_cast(unsigned, b); }
;     __device__ __forceinline__ void operator()(const f32x4 (&acc)[2][2][4][2], const pg8::Unit& u, int wr, int wc, int fr, int fq) const {
;     ...
;         const bool bf = isctx || base_f32, of = isctx || out_f32;
;         const float* bpf = isctx ? base_ctx : (const float*)base_lat; float* opf = isctx ? out_ctx : (float*)out_lat;
;         const bf16_t* bph = (const bf16_t*)base_lat; bf16_t* oph = (bf16_t*)out_lat;
; #pragma unroll
;         for (int ai = 0; ai < 2; ++ai)
; #pragma unroll
;             for (int m = 0; m < 4; ++m) { const size_t off = (size_t)(row0 + ai * 128 + m * 16) * DM + col0;
; #pragma unroll
;                 for (int bj = 0; bj < 2; ++bj) {
;                     f32x4 b0, b1;
;                     if (bf) { b0 = *(const f32x4*)(bpf + off + bj * 128); b1 = *(const f32x4*)(bpf + off + bj * 128 + 4); }
;                     else { const u32x4 w = *(const u32x4*)(bph + off + bj * 128);
;                         b0 = (f32x4){__uint_as_float(w.x << 16), __uint_as_float(w.x & 0xffff0000u), __uint_as_float(w.y << 16), __uint_as_float(w.y & 0xffff0000u)};
;                         b1 = (f32x4){__uint_as_float(w.z << 16), __uint_as_float(w.z & 0xffff0000u), __uint_as_float(w.w << 16), __uint_as_float(w.w & 0xffff0000u)}; }
;                     const f32x4 o0 = b0 + g[bj][0] * acc[ai][bj][m][0], o1 = b1 + g[bj][1] * acc[ai][bj][m][1];
;                     if (of) { *(f32x4*)(opf + off + bj * 128) = o0; *(f32x4*)(opf + off + bj * 128 + 4) = o1; }
;                     else { u32x4 w; w.x = pkbf(o0[0], o0[1]); w.y = pkbf(o0[2], o0[3]); w.z = pkbf(o1[0], o1[1]); w.w = pkbf(o1[2], o1[3]); *(u32x4*)(oph + off + bj * 128) = w; } } }
	v_lshlrev_b32_e32 v176, 16, v244
	v_and_b32_e32 v177, 0xffff0000, v244
	v_lshlrev_b32_e32 v178, 16, v245
	v_and_b32_e32 v179, 0xffff0000, v245
	v_lshlrev_b32_e32 v180, 16, v246
	v_and_b32_e32 v181, 0xffff0000, v246
	v_lshlrev_b32_e32 v182, 16, v247
	v_and_b32_e32 v183, 0xffff0000, v247
	v_pk_fma_f32 v[36:37], v[36:37], v[100:101], v[176:177]
	v_pk_fma_f32 v[38:39], v[38:39], v[102:103], v[178:179]
	v_pk_fma_f32 v[32:33], v[32:33], v[92:93], v[180:181]
	v_pk_fma_f32 v[34:35], v[34:35], v[94:95], v[182:183]
	v_cvt_pk_bf16_f32 v36, v36, v37
	v_cvt_pk_bf16_f32 v37, v38, v39
	v_cvt_pk_bf16_f32 v38, v32, v33
	v_cvt_pk_bf16_f32 v39, v34, v35
	global_store_dwordx4 v144, v[36:39], s[10:11] offset:256
	s_waitcnt vmcnt(15)
	v_lshlrev_b32_e32 v176, 16, v248
	v_and_b32_e32 v177, 0xffff0000, v248
	v_lshlrev_b32_e32 v178, 16, v249
	v_and_b32_e32 v179, 0xffff0000, v249
	v_lshlrev_b32_e32 v180, 16, v250
	v_and_b32_e32 v181, 0xffff0000, v250
	v_lshlrev_b32_e32 v182, 16, v251
	v_and_b32_e32 v183, 0xffff0000, v251
	v_pk_fma_f32 v[28:29], v[28:29], v[112:113], v[176:177]
	v_pk_fma_f32 v[30:31], v[30:31], v[114:115], v[178:179]
	v_pk_fma_f32 v[24:25], v[24:25], v[104:105], v[180:181]
	v_pk_fma_f32 v[26:27], v[26:27], v[106:107], v[182:183]
	s_add_u32 s10, s10, 0x8000
	s_addc_u32 s11, s11, 0
	v_cvt_pk_bf16_f32 v28, v28, v29
	v_cvt_pk_bf16_f32 v29, v30, v31
	v_cvt_pk_bf16_f32 v30, v24, v25
	v_cvt_pk_bf16_f32 v31, v26, v27
	global_store_dwordx4 v144, v[28:31], s[10:11]
	s_waitcnt vmcnt(15)
	v_lshlrev_b32_e32 v176, 16, v252
	v_and_b32_e32 v177, 0xffff0000, v252
	v_lshlrev_b32_e32 v178, 16, v253
	v_and_b32_e32 v179, 0xffff0000, v253
	v_lshlrev_b32_e32 v180, 16, v254
	v_and_b32_e32 v181, 0xffff0000, v254
	v_lshlrev_b32_e32 v182, 16, v255
	v_and_b32_e32 v183, 0xffff0000, v255
	v_pk_fma_f32 v[20:21], v[20:21], v[100:101], v[176:177]
	v_pk_fma_f32 v[22:23], v[22:23], v[102:103], v[178:179]
	v_pk_fma_f32 v[16:17], v[16:17], v[92:93], v[180:181]
	v_pk_fma_f32 v[18:19], v[18:19], v[94:95], v[182:183]
	v_cvt_pk_bf16_f32 v20, v20, v21
	v_cvt_pk_bf16_f32 v21, v22, v23
	v_cvt_pk_bf16_f32 v22, v16, v17
	v_cvt_pk_bf16_f32 v23, v18, v19
	global_store_dwordx4 v144, v[20:23], s[10:11] offset:256
	s_waitcnt vmcnt(15)
	v_lshlrev_b32_e32 v176, 16, v198
	v_and_b32_e32 v177, 0xffff0000, v198
	v_lshlrev_b32_e32 v178, 16, v199
	v_and_b32_e32 v179, 0xffff0000, v199
	v_lshlrev_b32_e32 v180, 16, v200
	v_and_b32_e32 v181, 0xffff0000, v200
	v_lshlrev_b32_e32 v182, 16, v201
	v_and_b32_e32 v183, 0xffff0000, v201
	v_pk_fma_f32 v[12:13], v[12:13], v[112:113], v[176:177]
	v_pk_fma_f32 v[14:15], v[14:15], v[114:115], v[178:179]
	v_pk_fma_f32 v[8:9], v[8:9], v[104:105], v[180:181]
	v_pk_fma_f32 v[10:11], v[10:11], v[106:107], v[182:183]
	s_add_u32 s10, s10, 0x8000
	s_addc_u32 s11, s11, 0
	v_cvt_pk_bf16_f32 v12, v12, v13
	v_cvt_pk_bf16_f32 v13, v14, v15
	v_cvt_pk_bf16_f32 v14, v8, v9
	v_cvt_pk_bf16_f32 v15, v10, v11
	global_store_dwordx4 v144, v[12:15], s[10:11]
	s_waitcnt vmcnt(14)
	v_lshlrev_b32_e32 v176, 16, v202
	v_and_b32_e32 v177, 0xffff0000, v202
	v_lshlrev_b32_e32 v178, 16, v203
	v_and_b32_e32 v179, 0xffff0000, v203
	v_lshlrev_b32_e32 v180, 16, v204
	v_and_b32_e32 v181, 0xffff0000, v204
	v_lshlrev_b32_e32 v182, 16, v205
	v_and_b32_e32 v183, 0xffff0000, v205
	v_pk_fma_f32 v[4:5], v[4:5], v[100:101], v[176:177]
	v_pk_fma_f32 v[6:7], v[6:7], v[102:103], v[178:179]
	v_pk_fma_f32 v[0:1], v[0:1], v[92:93], v[180:181]
	v_pk_fma_f32 v[2:3], v[2:3], v[94:95], v[182:183]
	v_cvt_pk_bf16_f32 v4, v4, v5
	v_cvt_pk_bf16_f32 v5, v6, v7
	v_cvt_pk_bf16_f32 v6, v0, v1
	v_cvt_pk_bf16_f32 v7, v2, v3
	global_store_dwordx4 v144, v[4:7], s[10:11] offset:256
	s_branch .LBB0_670

; __device__ __forceinline__ unsigned pkbf(float lo, float hi) { f32x2_t v = {lo, hi}; bf16x2_t b = __builtin_convertvector(v, bf16x2_t); return __builtin_bit_cast(unsigned, b); }
;     __device__ __forceinline__ void operator()(const f32x4 (&acc)[2][2][4][2], const pg8::Unit& u, int wr, int wc, int fr, int fq) const {
;     ...
;         const bool bf = isctx || base_f32, of = isctx || out_f32;
;         const float* bpf = isctx ? base_ctx : (const float*)base_lat; float* opf = isctx ? out_ctx : (float*)out_lat;
;         const bf16_t* bph = (const bf16_t*)base_lat; bf16_t* oph = (bf16_t*)out_lat;
; #pragma unroll
;         for (int ai = 0; ai < 2; ++ai)
; #pragma unroll
;             for (int m = 0; m < 4; ++m) { const size_t off = (size_t)(row0 + ai * 128 + m * 16) * DM + col0;
; #pragma unroll
;                 for (int bj = 0; bj < 2; ++bj) {
;                     f32x4 b0, b1;
;                     if (bf) { b0 = *(const f32x4*)(bpf + off + bj * 128); b1 = *(const f32x4*)(bpf + off + bj * 128 + 4); }
;                     else { const u32x4 w = *(const u32x4*)(bph + off + bj * 128);
;                         b0 = (f32x4){__uint_as_float(w.x << 16), __uint_as_float(w.x & 0xffff0000u), __uint_as_float(w.y << 16), __uint_as_float(w.y & 0xffff0000u)};
;                         b1 = (f32x4){__uint_as_float(w.z << 16), __uint_as_float(w.z & 0xffff0000u), __uint_as_float(w.w << 16), __uint_as_float(w.w & 0xffff0000u)}; }
;                     const f32x4 o0 = b0 + g[bj][0] * acc[ai][bj][m][0], o1 = b1 + g[bj][1] * acc[ai][bj][m][1];
;                     if (of) { *(f32x4*)(opf + off + bj * 128) = o0; *(f32x4*)(opf + off + bj * 128 + 4) = o1; }
;                     else { u32x4 w; w.x = pkbf(o0[0], o0[1]); w.y = pkbf(o0[2], o0[3]); w.z = pkbf(o1[0], o1[1]); w.w = pkbf(o1[2], o1[3]); *(u32x4*)(oph + off + bj * 128) = w; } } }
.LBB0_918:
	s_andn2_b64 vcc, exec, s[10:11]
	s_cbranch_vccnz .LBB0_1047
	s_and_b64 vcc, exec, s[0:1]
	s_cbranch_vccnz .Lepi_dn_orig
	v_readlane_b32 s26, v240, 19
	s_nop 0
	s_cmp_eq_u32 s26, 0
	s_cbranch_scc1 .Lepi_dn_bf
	v_lshl_add_u32 v144, v176, 10, v174
	v_lshlrev_b32_e32 v145, 2, v144
	v_lshlrev_b32_e32 v144, 1, v144
	s_mov_b32 s8, s70
	s_mov_b32 s9, s71
	v_readfirstlane_b32 s10, v158
	v_readfirstlane_b32 s11, v159
	s_nop 4
	global_load_dwordx4 v[198:201], v144, s[8:9]
	global_load_dwordx4 v[202:205], v144, s[8:9] offset:256
	s_add_u32 s8, s8, 0x8000
	s_addc_u32 s9, s9, 0
	global_load_dwordx4 v[206:209], v144, s[8:9]
	global_load_dwordx4 v[210:213], v144, s[8:9] offset:256
	s_add_u32 s8, s8, 0x8000
	s_addc_u32 s9, s9, 0
	global_load_dwordx4 v[214:217], v144, s[8:9]
	global_load_dwordx4 v[218:221], v144, s[8:9] offset:256
	s_add_u32 s8, s8, 0x8000
	s_addc_u32 s9, s9, 0
	global_load_dwordx4 v[222:225], v144, s[8:9]
	global_load_dwordx4 v[226:229], v144, s[8:9] offset:256
	s_add_u32 s8, s8, 0x28000
	s_addc_u32 s9, s9, 0
	global_load_dwordx4 v[190:193], v144, s[8:9]
	global_load_dwordx4 v[230:233], v144, s[8:9] offset:256
	s_add_u32 s8, s8, 0x8000
	s_addc_u32 s9, s9, 0
	global_load_dwordx4 v[234:237], v144, s[8:9]
	global_load_dwordx4 v[244:247], v144, s[8:9] offset:256
	s_add_u32 s8, s8, 0x8000
	s_addc_u32 s9, s9, 0
	global_load_dwordx4 v[248:251], v144, s[8:9]
	global_load_dwordx4 v[252:255], v144, s[8:9] offset:256
	s_waitcnt vmcnt(13)
	v_lshlrev_b32_e32 v178, 16, v198
	v_and_b32_e32 v179, 0xffff0000, v198
	v_lshlrev_b32_e32 v180, 16, v199
	v_and_b32_e32 v181, 0xffff0000, v199
	v_lshlrev_b32_e32 v182, 16, v200
	v_and_b32_e32 v183, 0xffff0000, v200
	v_lshlrev_b32_e32 v184, 16, v201
	v_and_b32_e32 v185, 0xffff0000, v201
	v_pk_fma_f32 v[140:141], v[140:141], v[100:101], v[178:179]
	v_pk_fma_f32 v[142:143], v[142:143], v[102:103], v[180:181]
	v_pk_fma_f32 v[136:137], v[136:137], v[96:97], v[182:183]
	v_pk_fma_f32 v[138:139], v[138:139], v[98:99], v[184:185]
	s_add_u32 s8, s8, 0x8000
	s_addc_u32 s9, s9, 0
	global_load_dwordx4 v[198:201], v144, s[8:9]
	global_store_dwordx4 v145, v[140:143], s[10:11]
	global_store_dwordx4 v145, v[136:139], s[10:11] offset:16
	s_waitcnt vmcnt(15)
	v_lshlrev_b32_e32 v178, 16, v202
	v_and_b32_e32 v179, 0xffff0000, v202
	v_lshlrev_b32_e32 v180, 16, v203
	v_and_b32_e32 v181, 0xffff0000, v203
	v_lshlrev_b32_e32 v182, 16, v204
	v_and_b32_e32 v183, 0xffff0000, v204
	v_lshlrev_b32_e32 v184, 16, v205
	v_and_b32_e32 v185, 0xffff0000, v205
	v_pk_fma_f32 v[132:133], v[132:133], v[88:89], v[178:179]
	v_pk_fma_f32 v[134:135], v[134:135], v[90:91], v[180:181]
	v_pk_fma_f32 v[128:129], v[128:129], v[80:81], v[182:183]
	v_pk_fma_f32 v[130:131], v[130:131], v[82:83], v[184:185]
	global_load_dwordx4 v[202:205], v144, s[8:9] offset:256
	global_store_dwordx4 v145, v[132:135], s[10:11] offset:512
	global_store_dwordx4 v145, v[128:131], s[10:11] offset:528
	s_waitcnt vmcnt(17)
	v_lshlrev_b32_e32 v178, 16, v206
	v_and_b32_e32 v179, 0xffff0000, v206
	v_lshlrev_b32_e32 v180, 16, v207
	v_and_b32_e32 v181, 0xffff0000, v207
	v_lshlrev_b32_e32 v182, 16, v208
	v_and_b32_e32 v183, 0xffff0000, v208
	v_lshlrev_b32_e32 v184, 16, v209
	v_and_b32_e32 v185, 0xffff0000, v209
	v_pk_fma_f32 v[124:125], v[124:125], v[100:101], v[178:179]
	v_pk_fma_f32 v[126:127], v[126:127], v[102:103], v[180:181]
	v_pk_fma_f32 v[120:121], v[120:121], v[96:97], v[182:183]
	v_pk_fma_f32 v[122:123], v[122:123], v[98:99], v[184:185]
	s_add_u32 s10, s10, 0x10000
	s_addc_u32 s11, s11, 0
	global_store_dwordx4 v145, v[124:127], s[10:11]
	global_store_dwordx4 v145, v[120:123], s[10:11] offset:16
	s_waitcnt vmcnt(18)
	v_lshlrev_b32_e32 v178, 16, v210
	v_and_b32_e32 v179, 0xffff0000, v210
	v_lshlrev_b32_e32 v180, 16, v211
	v_and_b32_e32 v181, 0xffff0000, v211
	v_lshlrev_b32_e32 v182, 16, v212
	v_and_b32_e32 v183, 0xffff0000, v212
	v_lshlrev_b32_e32 v184, 16, v213
	v_and_b32_e32 v185, 0xffff0000, v213
	v_pk_fma_f32 v[116:117], v[116:117], v[88:89], v[178:179]
	v_pk_fma_f32 v[118:119], v[118:119], v[90:91], v[180:181]
	v_pk_fma_f32 v[112:113], v[112:113], v[80:81], v[182:183]
	v_pk_fma_f32 v[114:115], v[114:115], v[82:83], v[184:185]
	global_store_dwordx4 v145, v[116:119], s[10:11] offset:512
	global_store_dwordx4 v145, v[112:115], s[10:11] offset:528
	s_waitcnt vmcnt(19)
	v_lshlrev_b32_e32 v178, 16, v214
	v_and_b32_e32 v179, 0xffff0000, v214
	v_lshlrev_b32_e32 v180, 16, v215
	v_and_b32_e32 v181, 0xffff0000, v215
	v_lshlrev_b32_e32 v182, 16, v216
	v_and_b32_e32 v183, 0xffff0000, v216
	v_lshlrev_b32_e32 v184, 16, v217
	v_and_b32_e32 v185, 0xffff0000, v217
	v_pk_fma_f32 v[108:109], v[108:109], v[100:101], v[178:179]
	v_pk_fma_f32 v[110:111], v[110:111], v[102:103], v[180:181]
	v_pk_fma_f32 v[104:105], v[104:105], v[96:97], v[182:183]
	v_pk_fma_f32 v[106:107], v[106:107], v[98:99], v[184:185]
	s_add_u32 s10, s10, 0x10000
	s_addc_u32 s11, s11, 0
	global_store_dwordx4 v145, v[108:111], s[10:11]
	global_store_dwordx4 v145, v[104:107], s[10:11] offset:16
	s_waitcnt vmcnt(20)
	v_lshlrev_b32_e32 v178, 16, v218
	v_and_b32_e32 v179, 0xffff0000, v218
	v_lshlrev_b32_e32 v180, 16, v219
	v_and_b32_e32 v181, 0xffff0000, v219
	v_lshlrev_b32_e32 v182, 16, v220
	v_and_b32_e32 v183, 0xffff0000, v220
	v_lshlrev_b32_e32 v184, 16, v221
	v_and_b32_e32 v185, 0xffff0000, v221
	v_pk_fma_f32 v[92:93], v[92:93], v[88:89], v[178:179]
	v_pk_fma_f32 v[94:95], v[94:95], v[90:91], v[180:181]
	v_pk_fma_f32 v[84:85], v[84:85], v[80:81], v[182:183]
	v_pk_fma_f32 v[86:87], v[86:87], v[82:83], v[184:185]
	global_store_dwordx4 v145, v[92:95], s[10:11] offset:512
	global_store_dwordx4 v145, v[84:87], s[10:11] offset:528
	s_waitcnt vmcnt(21)
; __device__ __forceinline__ unsigned pkbf(float lo, float hi) { f32x2_t v = {lo, hi}; bf16x2_t b = __builtin_convertvector(v, bf16x2_t); return __builtin_bit_cast(unsigned, b); }
;     __device__ __forceinline__ void operator()(const f32x4 (&acc)[2][2][4][2], const pg8::Unit& u, int wr, int wc, int fr, int fq) const {
;     ...
;         const bool bf = isctx || base_f32, of = isctx || out_f32;
;         const float* bpf = isctx ? base_ctx : (const float*)base_lat; float* opf = isctx ? out_ctx : (float*)out_lat;
;         const bf16_t* bph = (const bf16_t*)base_lat; bf16_t* oph = (bf16_t*)out_lat;
; #pragma unroll
;         for (int ai = 0; ai < 2; ++ai)
; #pragma unroll
;             for (int m = 0; m < 4; ++m) { const size_t off = (size_t)(row0 + ai * 128 + m * 16) * DM + col0;
; #pragma unroll
;                 for (int bj = 0; bj < 2; ++bj) {
;                     f32x4 b0, b1;
;                     if (bf) { b0 = *(const f32x4*)(bpf + off + bj * 128); b1 = *(const f32x4*)(bpf + off + bj * 128 + 4); }
;                     else { const u32x4 w = *(const u32x4*)(bph + off + bj * 128);
;                         b0 = (f32x4){__uint_as_float(w.x << 16), __uint_as_float(w.x & 0xffff0000u), __uint_as_float(w.y << 16), __uint_as_float(w.y & 0xffff0000u)};
;                         b1 = (f32x4){__uint_as_float(w.z << 16), __uint_as_float(w.z & 0xffff0000u), __uint_as_float(w.w << 16), __uint_as_float(w.w & 0xffff0000u)}; }
;                     const f32x4 o0 = b0 + g[bj][0] * acc[ai][bj][m][0], o1 = b1 + g[bj][1] * acc[ai][bj][m][1];
;                     if (of) { *(f32x4*)(opf + off + bj * 128) = o0; *(f32x4*)(opf + off + bj * 128 + 4) = o1; }
;                     else { u32x4 w; w.x = pkbf(o0[0], o0[1]); w.y = pkbf(o0[2], o0[3]); w.z = pkbf(o1[0], o1[1]); w.w = pkbf(o1[2], o1[3]); *(u32x4*)(oph + off + bj * 128) = w; } } }
	v_lshlrev_b32_e32 v178, 16, v222
	v_and_b32_e32 v179, 0xffff0000, v222
	v_lshlrev_b32_e32 v180, 16, v223
	v_and_b32_e32 v181, 0xffff0000, v223
	v_lshlrev_b32_e32 v182, 16, v224
	v_and_b32_e32 v183, 0xffff0000, v224
	v_lshlrev_b32_e32 v184, 16, v225
	v_and_b32_e32 v185, 0xffff0000, v225
	v_pk_fma_f32 v[76:77], v[76:77], v[100:101], v[178:179]
	v_pk_fma_f32 v[78:79], v[78:79], v[102:103], v[180:181]
	v_pk_fma_f32 v[72:73], v[72:73], v[96:97], v[182:183]
	v_pk_fma_f32 v[74:75], v[74:75], v[98:99], v[184:185]
	s_add_u32 s10, s10, 0x10000
	s_addc_u32 s11, s11, 0
	global_store_dwordx4 v145, v[76:79], s[10:11]
	global_store_dwordx4 v145, v[72:75], s[10:11] offset:16
	s_waitcnt vmcnt(22)
	v_lshlrev_b32_e32 v178, 16, v226
	v_and_b32_e32 v179, 0xffff0000, v226
	v_lshlrev_b32_e32 v180, 16, v227
	v_and_b32_e32 v181, 0xffff0000, v227
	v_lshlrev_b32_e32 v182, 16, v228
	v_and_b32_e32 v183, 0xffff0000, v228
	v_lshlrev_b32_e32 v184, 16, v229
	v_and_b32_e32 v185, 0xffff0000, v229
	v_pk_fma_f32 v[68:69], v[68:69], v[88:89], v[178:179]
	v_pk_fma_f32 v[70:71], v[70:71], v[90:91], v[180:181]
	v_pk_fma_f32 v[64:65], v[64:65], v[80:81], v[182:183]
	v_pk_fma_f32 v[66:67], v[66:67], v[82:83], v[184:185]
	global_store_dwordx4 v145, v[68:71], s[10:11] offset:512
	global_store_dwordx4 v145, v[64:67], s[10:11] offset:528
	s_waitcnt vmcnt(23)
	v_lshlrev_b32_e32 v178, 16, v190
	v_and_b32_e32 v179, 0xffff0000, v190
	v_lshlrev_b32_e32 v180, 16, v191
	v_and_b32_e32 v181, 0xffff0000, v191
	v_lshlrev_b32_e32 v182, 16, v192
	v_and_b32_e32 v183, 0xffff0000, v192
	v_lshlrev_b32_e32 v184, 16, v193
	v_and_b32_e32 v185, 0xffff0000, v193
	v_pk_fma_f32 v[60:61], v[60:61], v[100:101], v[178:179]
	v_pk_fma_f32 v[62:63], v[62:63], v[102:103], v[180:181]
	v_pk_fma_f32 v[56:57], v[56:57], v[96:97], v[182:183]
	v_pk_fma_f32 v[58:59], v[58:59], v[98:99], v[184:185]
	s_add_u32 s10, s10, 0x50000
	s_addc_u32 s11, s11, 0
	global_store_dwordx4 v145, v[60:63], s[10:11]
	global_store_dwordx4 v145, v[56:59], s[10:11] offset:16
	s_waitcnt vmcnt(24)
	v_lshlrev_b32_e32 v178, 16, v230
	v_and_b32_e32 v179, 0xffff0000, v230
	v_lshlrev_b32_e32 v180, 16, v231
	v_and_b32_e32 v181, 0xffff0000, v231
	v_lshlrev_b32_e32 v182, 16, v232
	v_and_b32_e32 v183, 0xffff0000, v232
	v_lshlrev_b32_e32 v184, 16, v233
	v_and_b32_e32 v185, 0xffff0000, v233
	v_pk_fma_f32 v[52:53], v[52:53], v[88:89], v[178:179]
	v_pk_fma_f32 v[54:55], v[54:55], v[90:91], v[180:181]
	v_pk_fma_f32 v[48:49], v[48:49], v[80:81], v[182:183]
	v_pk_fma_f32 v[50:51], v[50:51], v[82:83], v[184:185]
	global_store_dwordx4 v145, v[52:55], s[10:11] offset:512
	global_store_dwordx4 v145, v[48:51], s[10:11] offset:528
	s_waitcnt vmcnt(25)
	v_lshlrev_b32_e32 v178, 16, v234
	v_and_b32_e32 v179, 0xffff0000, v234
	v_lshlrev_b32_e32 v180, 16, v235
	v_and_b32_e32 v181, 0xffff0000, v235
	v_lshlrev_b32_e32 v182, 16, v236
	v_and_b32_e32 v183, 0xffff0000, v236
	v_lshlrev_b32_e32 v184, 16, v237
	v_and_b32_e32 v185, 0xffff0000, v237
	v_pk_fma_f32 v[44:45], v[44:45], v[100:101], v[178:179]
	v_pk_fma_f32 v[46:47], v[46:47], v[102:103], v[180:181]
	v_pk_fma_f32 v[40:41], v[40:41], v[96:97], v[182:183]
	v_pk_fma_f32 v[42:43], v[42:43], v[98:99], v[184:185]
	s_add_u32 s10, s10, 0x10000
	s_addc_u32 s11, s11, 0
	global_store_dwordx4 v145, v[44:47], s[10:11]
	global_store_dwordx4 v145, v[40:43], s[10:11] offset:16
	s_waitcnt vmcnt(26)
	v_lshlrev_b32_e32 v178, 16, v244
	v_and_b32_e32 v179, 0xffff0000, v244
	v_lshlrev_b32_e32 v180, 16, v245
	v_and_b32_e32 v181, 0xffff0000, v245
	v_lshlrev_b32_e32 v182, 16, v246
	v_and_b32_e32 v183, 0xffff0000, v246
	v_lshlrev_b32_e32 v184, 16, v247
	v_and_b32_e32 v185, 0xffff0000, v247
	v_pk_fma_f32 v[36:37], v[36:37], v[88:89], v[178:179]
	v_pk_fma_f32 v[38:39], v[38:39], v[90:91], v[180:181]
	v_pk_fma_f32 v[32:33], v[32:33], v[80:81], v[182:183]
	v_pk_fma_f32 v[34:35], v[34:35], v[82:83], v[184:185]
	global_store_dwordx4 v145, v[36:39], s[10:11] offset:512
	global_store_dwordx4 v145, v[32:35], s[10:11] offset:528
	s_waitcnt vmcnt(27)
	v_lshlrev_b32_e32 v178, 16, v248
	v_and_b32_e32 v179, 0xffff0000, v248
	v_lshlrev_b32_e32 v180, 16, v249
	v_and_b32_e32 v181, 0xffff0000, v249
	v_lshlrev_b32_e32 v182, 16, v250
	v_and_b32_e32 v183, 0xffff0000, v250
	v_lshlrev_b32_e32 v184, 16, v251
	v_and_b32_e32 v185, 0xffff0000, v251
	v_pk_fma_f32 v[28:29], v[28:29], v[100:101], v[178:179]
	v_pk_fma_f32 v[30:31], v[30:31], v[102:103], v[180:181]
	v_pk_fma_f32 v[24:25], v[24:25], v[96:97], v[182:183]
	v_pk_fma_f32 v[26:27], v[26:27], v[98:99], v[184:185]
	s_add_u32 s10, s10, 0x10000
	s_addc_u32 s11, s11, 0
	global_store_dwordx4 v145, v[28:31], s[10:11]
	global_store_dwordx4 v145, v[24:27], s[10:11] offset:16
	s_waitcnt vmcnt(28)
	v_lshlrev_b32_e32 v178, 16, v252
	v_and_b32_e32 v179, 0xffff0000, v252
	v_lshlrev_b32_e32 v180, 16, v253
	v_and_b32_e32 v181, 0xffff0000, v253
	v_lshlrev_b32_e32 v182, 16, v254
	v_and_b32_e32 v183, 0xffff0000, v254
	v_lshlrev_b32_e32 v184, 16, v255
	v_and_b32_e32 v185, 0xffff0000, v255
	v_pk_fma_f32 v[20:21], v[20:21], v[88:89], v[178:179]
	v_pk_fma_f32 v[22:23], v[22:23], v[90:91], v[180:181]
	v_pk_fma_f32 v[16:17], v[16:17], v[80:81], v[182:183]
	v_pk_fma_f32 v[18:19], v[18:19], v[82:83], v[184:185]
	global_store_dwordx4 v145, v[20:23], s[10:11] offset:512
	global_store_dwordx4 v145, v[16:19], s[10:11] offset:528
	s_waitcnt vmcnt(29)
	v_lshlrev_b32_e32 v178, 16, v198
	v_and_b32_e32 v179, 0xffff0000, v198
	v_lshlrev_b32_e32 v180, 16, v199
	v_and_b32_e32 v181, 0xffff0000, v199
	v_lshlrev_b32_e32 v182, 16, v200
	v_and_b32_e32 v183, 0xffff0000, v200
	v_lshlrev_b32_e32 v184, 16, v201
	v_and_b32_e32 v185, 0xffff0000, v201
	v_pk_fma_f32 v[12:13], v[12:13], v[100:101], v[178:179]
	v_pk_fma_f32 v[14:15], v[14:15], v[102:103], v[180:181]
	v_pk_fma_f32 v[8:9], v[8:9], v[96:97], v[182:183]
	v_pk_fma_f32 v[10:11], v[10:11], v[98:99], v[184:185]
	s_add_u32 s10, s10, 0x10000
	s_addc_u32 s11, s11, 0
	global_store_dwordx4 v145, v[12:15], s[10:11]
	global_store_dwordx4 v145, v[8:11], s[10:11] offset:16
	s_waitcnt vmcnt(28)
	v_lshlrev_b32_e32 v178, 16, v202
	v_and_b32_e32 v179, 0xffff0000, v202
	v_lshlrev_b32_e32 v180, 16, v203
	v_and_b32_e32 v181, 0xffff0000, v203
	v_lshlrev_b32_e32 v182, 16, v204
	v_and_b32_e32 v183, 0xffff0000, v204
	v_lshlrev_b32_e32 v184, 16, v205
	v_and_b32_e32 v185, 0xffff0000, v205
	v_pk_fma_f32 v[4:5], v[4:5], v[88:89], v[178:179]
	v_pk_fma_f32 v[6:7], v[6:7], v[90:91], v[180:181]
	v_pk_fma_f32 v[0:1], v[0:1], v[80:81], v[182:183]
	v_pk_fma_f32 v[2:3], v[2:3], v[82:83], v[184:185]
	global_store_dwordx4 v145, v[4:7], s[10:11] offset:512
	global_store_dwordx4 v145, v[0:3], s[10:11] offset:528
	s_branch .LBB0_1047
; __device__ __forceinline__ unsigned pkbf(float lo, float hi) { f32x2_t v = {lo, hi}; bf16x2_t b = __builtin_convertvector(v, bf16x2_t); return __builtin_bit_cast(unsigned, b); }
;     __device__ __forceinline__ void operator()(const f32x4 (&acc)[2][2][4][2], const pg8::Unit& u, int wr, int wc, int fr, int fq) const {
;     ...
;         const bool bf = isctx || base_f32, of = isctx || out_f32;
;         const float* bpf = isctx ? base_ctx : (const float*)base_lat; float* opf = isctx ? out_ctx : (float*)out_lat;
;         const bf16_t* bph = (const bf16_t*)base_lat; bf16_t* oph = (bf16_t*)out_lat;
; #pragma unroll
;         for (int ai = 0; ai < 2; ++ai)
; #pragma unroll
;             for (int m = 0; m < 4; ++m) { const size_t off = (size_t)(row0 + ai * 128 + m * 16) * DM + col0;
; #pragma unroll
;                 for (int bj = 0; bj < 2; ++bj) {
;                     f32x4 b0, b1;
;                     if (bf) { b0 = *(const f32x4*)(bpf + off + bj * 128); b1 = *(const f32x4*)(bpf + off + bj * 128 + 4); }
;                     else { const u32x4 w = *(const u32x4*)(bph + off + bj * 128);
;                         b0 = (f32x4){__uint_as_float(w.x << 16), __uint_as_float(w.x & 0xffff0000u), __uint_as_float(w.y << 16), __uint_as_float(w.y & 0xffff0000u)};
;                         b1 = (f32x4){__uint_as_float(w.z << 16), __uint_as_float(w.z & 0xffff0000u), __uint_as_float(w.w << 16), __uint_as_float(w.w & 0xffff0000u)}; }
;                     const f32x4 o0 = b0 + g[bj][0] * acc[ai][bj][m][0], o1 = b1 + g[bj][1] * acc[ai][bj][m][1];
;                     if (of) { *(f32x4*)(opf + off + bj * 128) = o0; *(f32x4*)(opf + off + bj * 128 + 4) = o1; }
;                     else { u32x4 w; w.x = pkbf(o0[0], o0[1]); w.y = pkbf(o0[2], o0[3]); w.z = pkbf(o1[0], o1[1]); w.w = pkbf(o1[2], o1[3]); *(u32x4*)(oph + off + bj * 128) = w; } } }
.Lepi_dn_bf:
	v_lshl_add_u32 v144, v176, 10, v174
	v_lshlrev_b32_e32 v145, 2, v144
	v_lshlrev_b32_e32 v144, 1, v144
	s_mov_b32 s8, s70
	s_mov_b32 s9, s71
	v_readfirstlane_b32 s10, v158
	v_readfirstlane_b32 s11, v159
	s_nop 4
	global_load_dwordx4 v[198:201], v144, s[8:9]
	global_load_dwordx4 v[202:205], v144, s[8:9] offset:256
	s_add_u32 s8, s8, 0x8000
	s_addc_u32 s9, s9, 0
	global_load_dwordx4 v[206:209], v144, s[8:9]
	global_load_dwordx4 v[210:213], v144, s[8:9] offset:256
	s_add_u32 s8, s8, 0x8000
	s_addc_u32 s9, s9, 0
	global_load_dwordx4 v[214:217], v144, s[8:9]
	global_load_dwordx4 v[218:221], v144, s[8:9] offset:256
	s_add_u32 s8, s8, 0x8000
	s_addc_u32 s9, s9, 0
	global_load_dwordx4 v[222:225], v144, s[8:9]
	global_load_dwordx4 v[226:229], v144, s[8:9] offset:256
	s_add_u32 s8, s8, 0x28000
	s_addc_u32 s9, s9, 0
	global_load_dwordx4 v[190:193], v144, s[8:9]
	global_load_dwordx4 v[230:233], v144, s[8:9] offset:256
	s_add_u32 s8, s8, 0x8000
	s_addc_u32 s9, s9, 0
	global_load_dwordx4 v[234:237], v144, s[8:9]
	global_load_dwordx4 v[244:247], v144, s[8:9] offset:256
	s_add_u32 s8, s8, 0x8000
	s_addc_u32 s9, s9, 0
	global_load_dwordx4 v[248:251], v144, s[8:9]
	global_load_dwordx4 v[252:255], v144, s[8:9] offset:256
	s_waitcnt vmcnt(13)
	v_lshlrev_b32_e32 v178, 16, v198
	v_and_b32_e32 v179, 0xffff0000, v198
	v_lshlrev_b32_e32 v180, 16, v199
	v_and_b32_e32 v181, 0xffff0000, v199
	v_lshlrev_b32_e32 v182, 16, v200
	v_and_b32_e32 v183, 0xffff0000, v200
	v_lshlrev_b32_e32 v184, 16, v201
	v_and_b32_e32 v185, 0xffff0000, v201
	v_pk_fma_f32 v[140:141], v[140:141], v[100:101], v[178:179]
	v_pk_fma_f32 v[142:143], v[142:143], v[102:103], v[180:181]
	v_pk_fma_f32 v[136:137], v[136:137], v[96:97], v[182:183]
	v_pk_fma_f32 v[138:139], v[138:139], v[98:99], v[184:185]
	s_add_u32 s8, s8, 0x8000
	s_addc_u32 s9, s9, 0
	global_load_dwordx4 v[198:201], v144, s[8:9]
	v_cvt_pk_bf16_f32 v140, v140, v141
	v_cvt_pk_bf16_f32 v141, v142, v143
	v_cvt_pk_bf16_f32 v142, v136, v137
	v_cvt_pk_bf16_f32 v143, v138, v139
	global_store_dwordx4 v144, v[140:143], s[10:11]
	s_waitcnt vmcnt(14)
	v_lshlrev_b32_e32 v178, 16, v202
	v_and_b32_e32 v179, 0xffff0000, v202
	v_lshlrev_b32_e32 v180, 16, v203
	v_and_b32_e32 v181, 0xffff0000, v203
	v_lshlrev_b32_e32 v182, 16, v204
	v_and_b32_e32 v183, 0xffff0000, v204
	v_lshlrev_b32_e32 v184, 16, v205
	v_and_b32_e32 v185, 0xffff0000, v205
	v_pk_fma_f32 v[132:133], v[132:133], v[88:89], v[178:179]
	v_pk_fma_f32 v[134:135], v[134:135], v[90:91], v[180:181]
	v_pk_fma_f32 v[128:129], v[128:129], v[80:81], v[182:183]
	v_pk_fma_f32 v[130:131], v[130:131], v[82:83], v[184:185]
	global_load_dwordx4 v[202:205], v144, s[8:9] offset:256
	v_cvt_pk_bf16_f32 v132, v132, v133
	v_cvt_pk_bf16_f32 v133, v134, v135
	v_cvt_pk_bf16_f32 v134, v128, v129
	v_cvt_pk_bf16_f32 v135, v130, v131
	global_store_dwordx4 v144, v[132:135], s[10:11] offset:256
	s_waitcnt vmcnt(15)
	v_lshlrev_b32_e32 v178, 16, v206
	v_and_b32_e32 v179, 0xffff0000, v206
	v_lshlrev_b32_e32 v180, 16, v207
	v_and_b32_e32 v181, 0xffff0000, v207
	v_lshlrev_b32_e32 v182, 16, v208
	v_and_b32_e32 v183, 0xffff0000, v208
	v_lshlrev_b32_e32 v184, 16, v209
	v_and_b32_e32 v185, 0xffff0000, v209
	v_pk_fma_f32 v[124:125], v[124:125], v[100:101], v[178:179]
	v_pk_fma_f32 v[126:127], v[126:127], v[102:103], v[180:181]
	v_pk_fma_f32 v[120:121], v[120:121], v[96:97], v[182:183]
	v_pk_fma_f32 v[122:123], v[122:123], v[98:99], v[184:185]
	s_add_u32 s10, s10, 0x8000
	s_addc_u32 s11, s11, 0
	v_cvt_pk_bf16_f32 v124, v124, v125
	v_cvt_pk_bf16_f32 v125, v126, v127
	v_cvt_pk_bf16_f32 v126, v120, v121
	v_cvt_pk_bf16_f32 v127, v122, v123
	global_store_dwordx4 v144, v[124:127], s[10:11]
	s_waitcnt vmcnt(15)
	v_lshlrev_b32_e32 v178, 16, v210
	v_and_b32_e32 v179, 0xffff0000, v210
	v_lshlrev_b32_e32 v180, 16, v211
	v_and_b32_e32 v181, 0xffff0000, v211
	v_lshlrev_b32_e32 v182, 16, v212
	v_and_b32_e32 v183, 0xffff0000, v212
	v_lshlrev_b32_e32 v184, 16, v213
	v_and_b32_e32 v185, 0xffff0000, v213
	v_pk_fma_f32 v[116:117], v[116:117], v[88:89], v[178:179]
	v_pk_fma_f32 v[118:119], v[118:119], v[90:91], v[180:181]
	v_pk_fma_f32 v[112:113], v[112:113], v[80:81], v[182:183]
	v_pk_fma_f32 v[114:115], v[114:115], v[82:83], v[184:185]
	v_cvt_pk_bf16_f32 v116, v116, v117
	v_cvt_pk_bf16_f32 v117, v118, v119
	v_cvt_pk_bf16_f32 v118, v112, v113
	v_cvt_pk_bf16_f32 v119, v114, v115
	global_store_dwordx4 v144, v[116:119], s[10:11] offset:256
	s_waitcnt vmcnt(15)
	v_lshlrev_b32_e32 v178, 16, v214
	v_and_b32_e32 v179, 0xffff0000, v214
	v_lshlrev_b32_e32 v180, 16, v215
	v_and_b32_e32 v181, 0xffff0000, v215
	v_lshlrev_b32_e32 v182, 16, v216
	v_and_b32_e32 v183, 0xffff0000, v216
	v_lshlrev_b32_e32 v184, 16, v217
	v_and_b32_e32 v185, 0xffff0000, v217
	v_pk_fma_f32 v[108:109], v[108:109], v[100:101], v[178:179]
	v_pk_fma_f32 v[110:111], v[110:111], v[102:103], v[180:181]
	v_pk_fma_f32 v[104:105], v[104:105], v[96:97], v[182:183]
	v_pk_fma_f32 v[106:107], v[106:107], v[98:99], v[184:185]
	s_add_u32 s10, s10, 0x8000
	s_addc_u32 s11, s11, 0
	v_cvt_pk_bf16_f32 v108, v108, v109
	v_cvt_pk_bf16_f32 v109, v110, v111
	v_cvt_pk_bf16_f32 v110, v104, v105
	v_cvt_pk_bf16_f32 v111, v106, v107
	global_store_dwordx4 v144, v[108:111], s[10:11]
	s_waitcnt vmcnt(15)
	v_lshlrev_b32_e32 v178, 16, v218
	v_and_b32_e32 v179, 0xffff0000, v218
	v_lshlrev_b32_e32 v180, 16, v219
	v_and_b32_e32 v181, 0xffff0000, v219
	v_lshlrev_b32_e32 v182, 16, v220
	v_and_b32_e32 v183, 0xffff0000, v220
	v_lshlrev_b32_e32 v184, 16, v221
	v_and_b32_e32 v185, 0xffff0000, v221
	v_pk_fma_f32 v[92:93], v[92:93], v[88:89], v[178:179]
	v_pk_fma_f32 v[94:95], v[94:95], v[90:91], v[180:181]
	v_pk_fma_f32 v[84:85], v[84:85], v[80:81], v[182:183]
	v_pk_fma_f32 v[86:87], v[86:87], v[82:83], v[184:185]
	v_cvt_pk_bf16_f32 v92, v92, v93
	v_cvt_pk_bf16_f32 v93, v94, v95
	v_cvt_pk_bf16_f32 v94, v84, v85
	v_cvt_pk_bf16_f32 v95, v86, v87
	global_store_dwordx4 v144, v[92:95], s[10:11] offset:256
	s_waitcnt vmcnt(15)
; __device__ __forceinline__ unsigned pkbf(float lo, float hi) { f32x2_t v = {lo, hi}; bf16x2_t b = __builtin_convertvector(v, bf16x2_t); return __builtin_bit_cast(unsigned, b); }
;     __device__ __forceinline__ void operator()(const f32x4 (&acc)[2][2][4][2], const pg8::Unit& u, int wr, int wc, int fr, int fq) const {
;     ...
;         const bool bf = isctx || base_f32, of = isctx || out_f32;
;         const float* bpf = isctx ? base_ctx : (const float*)base_lat; float* opf = isctx ? out_ctx : (float*)out_lat;
;         const bf16_t* bph = (const bf16_t*)base_lat; bf16_t* oph = (bf16_t*)out_lat;
; #pragma unroll
;         for (int ai = 0; ai < 2; ++ai)
; #pragma unroll
;             for (int m = 0; m < 4; ++m) { const size_t off = (size_t)(row0 + ai * 128 + m * 16) * DM + col0;
; #pragma unroll
;                 for (int bj = 0; bj < 2; ++bj) {
;                     f32x4 b0, b1;
;                     if (bf) { b0 = *(const f32x4*)(bpf + off + bj * 128); b1 = *(const f32x4*)(bpf + off + bj * 128 + 4); }
;                     else { const u32x4 w = *(const u32x4*)(bph + off + bj * 128);
;                         b0 = (f32x4){__uint_as_float(w.x << 16), __uint_as_float(w.x & 0xffff0000u), __uint_as_float(w.y << 16), __uint_as_float(w.y & 0xffff0000u)};
;                         b1 = (f32x4){__uint_as_float(w.z << 16), __uint_as_float(w.z & 0xffff0000u), __uint_as_float(w.w << 16), __uint_as_float(w.w & 0xffff0000u)}; }
;                     const f32x4 o0 = b0 + g[bj][0] * acc[ai][bj][m][0], o1 = b1 + g[bj][1] * acc[ai][bj][m][1];
;                     if (of) { *(f32x4*)(opf + off + bj * 128) = o0; *(f32x4*)(opf + off + bj * 128 + 4) = o1; }
;                     else { u32x4 w; w.x = pkbf(o0[0], o0[1]); w.y = pkbf(o0[2], o0[3]); w.z = pkbf(o1[0], o1[1]); w.w = pkbf(o1[2], o1[3]); *(u32x4*)(oph + off + bj * 128) = w; } } }
	v_lshlrev_b32_e32 v178, 16, v222
	v_and_b32_e32 v179, 0xffff0000, v222
	v_lshlrev_b32_e32 v180, 16, v223
	v_and_b32_e32 v181, 0xffff0000, v223
	v_lshlrev_b32_e32 v182, 16, v224
	v_and_b32_e32 v183, 0xffff0000, v224
	v_lshlrev_b32_e32 v184, 16, v225
	v_and_b32_e32 v185, 0xffff0000, v225
	v_pk_fma_f32 v[76:77], v[76:77], v[100:101], v[178:179]
	v_pk_fma_f32 v[78:79], v[78:79], v[102:103], v[180:181]
	v_pk_fma_f32 v[72:73], v[72:73], v[96:97], v[182:183]
	v_pk_fma_f32 v[74:75], v[74:75], v[98:99], v[184:185]
	s_add_u32 s10, s10, 0x8000
	s_addc_u32 s11, s11, 0
	v_cvt_pk_bf16_f32 v76, v76, v77
	v_cvt_pk_bf16_f32 v77, v78, v79
	v_cvt_pk_bf16_f32 v78, v72, v73
	v_cvt_pk_bf16_f32 v79, v74, v75
	global_store_dwordx4 v144, v[76:79], s[10:11]
	s_waitcnt vmcnt(15)
	v_lshlrev_b32_e32 v178, 16, v226
	v_and_b32_e32 v179, 0xffff0000, v226
	v_lshlrev_b32_e32 v180, 16, v227
	v_and_b32_e32 v181, 0xffff0000, v227
	v_lshlrev_b32_e32 v182, 16, v228
	v_and_b32_e32 v183, 0xffff0000, v228
	v_lshlrev_b32_e32 v184, 16, v229
	v_and_b32_e32 v185, 0xffff0000, v229
	v_pk_fma_f32 v[68:69], v[68:69], v[88:89], v[178:179]
	v_pk_fma_f32 v[70:71], v[70:71], v[90:91], v[180:181]
	v_pk_fma_f32 v[64:65], v[64:65], v[80:81], v[182:183]
	v_pk_fma_f32 v[66:67], v[66:67], v[82:83], v[184:185]
	v_cvt_pk_bf16_f32 v68, v68, v69
	v_cvt_pk_bf16_f32 v69, v70, v71
	v_cvt_pk_bf16_f32 v70, v64, v65
	v_cvt_pk_bf16_f32 v71, v66, v67
	global_store_dwordx4 v144, v[68:71], s[10:11] offset:256
	s_waitcnt vmcnt(15)
	v_lshlrev_b32_e32 v178, 16, v190
	v_and_b32_e32 v179, 0xffff0000, v190
	v_lshlrev_b32_e32 v180, 16, v191
	v_and_b32_e32 v181, 0xffff0000, v191
	v_lshlrev_b32_e32 v182, 16, v192
	v_and_b32_e32 v183, 0xffff0000, v192
	v_lshlrev_b32_e32 v184, 16, v193
	v_and_b32_e32 v185, 0xffff0000, v193
	v_pk_fma_f32 v[60:61], v[60:61], v[100:101], v[178:179]
	v_pk_fma_f32 v[62:63], v[62:63], v[102:103], v[180:181]
	v_pk_fma_f32 v[56:57], v[56:57], v[96:97], v[182:183]
	v_pk_fma_f32 v[58:59], v[58:59], v[98:99], v[184:185]
	s_add_u32 s10, s10, 0x28000
	s_addc_u32 s11, s11, 0
	v_cvt_pk_bf16_f32 v60, v60, v61
	v_cvt_pk_bf16_f32 v61, v62, v63
	v_cvt_pk_bf16_f32 v62, v56, v57
	v_cvt_pk_bf16_f32 v63, v58, v59
	global_store_dwordx4 v144, v[60:63], s[10:11]
	s_waitcnt vmcnt(15)
	v_lshlrev_b32_e32 v178, 16, v230
	v_and_b32_e32 v179, 0xffff0000, v230
	v_lshlrev_b32_e32 v180, 16, v231
	v_and_b32_e32 v181, 0xffff0000, v231
	v_lshlrev_b32_e32 v182, 16, v232
	v_and_b32_e32 v183, 0xffff0000, v232
	v_lshlrev_b32_e32 v184, 16, v233
	v_and_b32_e32 v185, 0xffff0000, v233
	v_pk_fma_f32 v[52:53], v[52:53], v[88:89], v[178:179]
	v_pk_fma_f32 v[54:55], v[54:55], v[90:91], v[180:181]
	v_pk_fma_f32 v[48:49], v[48:49], v[80:81], v[182:183]
	v_pk_fma_f32 v[50:51], v[50:51], v[82:83], v[184:185]
	v_cvt_pk_bf16_f32 v52, v52, v53
	v_cvt_pk_bf16_f32 v53, v54, v55
	v_cvt_pk_bf16_f32 v54, v48, v49
	v_cvt_pk_bf16_f32 v55, v50, v51
	global_store_dwordx4 v144, v[52:55], s[10:11] offset:256
	s_waitcnt vmcnt(15)
	v_lshlrev_b32_e32 v178, 16, v234
	v_and_b32_e32 v179, 0xffff0000, v234
	v_lshlrev_b32_e32 v180, 16, v235
	v_and_b32_e32 v181, 0xffff0000, v235
	v_lshlrev_b32_e32 v182, 16, v236
	v_and_b32_e32 v183, 0xffff0000, v236
	v_lshlrev_b32_e32 v184, 16, v237
	v_and_b32_e32 v185, 0xffff0000, v237
	v_pk_fma_f32 v[44:45], v[44:45], v[100:101], v[178:179]
	v_pk_fma_f32 v[46:47], v[46:47], v[102:103], v[180:181]
	v_pk_fma_f32 v[40:41], v[40:41], v[96:97], v[182:183]
	v_pk_fma_f32 v[42:43], v[42:43], v[98:99], v[184:185]
	s_add_u32 s10, s10, 0x8000
	s_addc_u32 s11, s11, 0
	v_cvt_pk_bf16_f32 v44, v44, v45
	v_cvt_pk_bf16_f32 v45, v46, v47
	v_cvt_pk_bf16_f32 v46, v40, v41
	v_cvt_pk_bf16_f32 v47, v42, v43
	global_store_dwordx4 v144, v[44:47], s[10:11]
	s_waitcnt vmcnt(15)
; __device__ __forceinline__ unsigned pkbf(float lo, float hi) { f32x2_t v = {lo, hi}; bf16x2_t b = __builtin_convertvector(v, bf16x2_t); return __builtin_bit_cast(unsigned, b); }
;     __device__ __forceinline__ void operator()(const f32x4 (&acc)[2][2][4][2], const pg8::Unit& u, int wr, int wc, int fr, int fq) const {
;     ...
;         const bool bf = isctx || base_f32, of = isctx || out_f32;
;         const float* bpf = isctx ? base_ctx : (const float*)base_lat; float* opf = isctx ? out_ctx : (float*)out_lat;
;         const bf16_t* bph = (const bf16_t*)base_lat; bf16_t* oph = (bf16_t*)out_lat;
; #pragma unroll
;         for (int ai = 0; ai < 2; ++ai)
; #pragma unroll
;             for (int m = 0; m < 4; ++m) { const size_t off = (size_t)(row0 + ai * 128 + m * 16) * DM + col0;
; #pragma unroll
;                 for (int bj = 0; bj < 2; ++bj) {
;                     f32x4 b0, b1;
;                     if (bf) { b0 = *(const f32x4*)(bpf + off + bj * 128); b1 = *(const f32x4*)(bpf + off + bj * 128 + 4); }
;                     else { const u32x4 w = *(const u32x4*)(bph + off + bj * 128);
;                         b0 = (f32x4){__uint_as_float(w.x << 16), __uint_as_float(w.x & 0xffff0000u), __uint_as_float(w.y << 16), __uint_as_float(w.y & 0xffff0000u)};
;                         b1 = (f32x4){__uint_as_float(w.z << 16), __uint_as_float(w.z & 0xffff0000u), __uint_as_float(w.w << 16), __uint_as_float(w.w & 0xffff0000u)}; }
;                     const f32x4 o0 = b0 + g[bj][0] * acc[ai][bj][m][0], o1 = b1 + g[bj][1] * acc[ai][bj][m][1];
;                     if (of) { *(f32x4*)(opf + off + bj * 128) = o0; *(f32x4*)(opf + off + bj * 128 + 4) = o1; }
;                     else { u32x4 w; w.x = pkbf(o0[0], o0[1]); w.y = pkbf(o0[2], o0[3]); w.z = pkbf(o1[0], o1[1]); w.w = pkbf(o1[2], o1[3]); *(u32x4*)(oph + off + bj * 128) = w; } } }
	v_lshlrev_b32_e32 v178, 16, v244
	v_and_b32_e32 v179, 0xffff0000, v244
	v_lshlrev_b32_e32 v180, 16, v245
	v_and_b32_e32 v181, 0xffff0000, v245
	v_lshlrev_b32_e32 v182, 16, v246
	v_and_b32_e32 v183, 0xffff0000, v246
	v_lshlrev_b32_e32 v184, 16, v247
	v_and_b32_e32 v185, 0xffff0000, v247
	v_pk_fma_f32 v[36:37], v[36:37], v[88:89], v[178:179]
	v_pk_fma_f32 v[38:39], v[38:39], v[90:91], v[180:181]
	v_pk_fma_f32 v[32:33], v[32:33], v[80:81], v[182:183]
	v_pk_fma_f32 v[34:35], v[34:35], v[82:83], v[184:185]
	v_cvt_pk_bf16_f32 v36, v36, v37
	v_cvt_pk_bf16_f32 v37, v38, v39
	v_cvt_pk_bf16_f32 v38, v32, v33
	v_cvt_pk_bf16_f32 v39, v34, v35
	global_store_dwordx4 v144, v[36:39], s[10:11] offset:256
	s_waitcnt vmcnt(15)
	v_lshlrev_b32_e32 v178, 16, v248
	v_and_b32_e32 v179, 0xffff0000, v248
	v_lshlrev_b32_e32 v180, 16, v249
	v_and_b32_e32 v181, 0xffff0000, v249
	v_lshlrev_b32_e32 v182, 16, v250
	v_and_b32_e32 v183, 0xffff0000, v250
	v_lshlrev_b32_e32 v184, 16, v251
	v_and_b32_e32 v185, 0xffff0000, v251
	v_pk_fma_f32 v[28:29], v[28:29], v[100:101], v[178:179]
	v_pk_fma_f32 v[30:31], v[30:31], v[102:103], v[180:181]
	v_pk_fma_f32 v[24:25], v[24:25], v[96:97], v[182:183]
	v_pk_fma_f32 v[26:27], v[26:27], v[98:99], v[184:185]
	s_add_u32 s10, s10, 0x8000
	s_addc_u32 s11, s11, 0
	v_cvt_pk_bf16_f32 v28, v28, v29
	v_cvt_pk_bf16_f32 v29, v30, v31
	v_cvt_pk_bf16_f32 v30, v24, v25
	v_cvt_pk_bf16_f32 v31, v26, v27
	global_store_dwordx4 v144, v[28:31], s[10:11]
	s_waitcnt vmcnt(15)
	v_lshlrev_b32_e32 v178, 16, v252
	v_and_b32_e32 v179, 0xffff0000, v252
	v_lshlrev_b32_e32 v180, 16, v253
	v_and_b32_e32 v181, 0xffff0000, v253
	v_lshlrev_b32_e32 v182, 16, v254
	v_and_b32_e32 v183, 0xffff0000, v254
	v_lshlrev_b32_e32 v184, 16, v255
	v_and_b32_e32 v185, 0xffff0000, v255
	v_pk_fma_f32 v[20:21], v[20:21], v[88:89], v[178:179]
	v_pk_fma_f32 v[22:23], v[22:23], v[90:91], v[180:181]
	v_pk_fma_f32 v[16:17], v[16:17], v[80:81], v[182:183]
	v_pk_fma_f32 v[18:19], v[18:19], v[82:83], v[184:185]
	v_cvt_pk_bf16_f32 v20, v20, v21
	v_cvt_pk_bf16_f32 v21, v22, v23
	v_cvt_pk_bf16_f32 v22, v16, v17
	v_cvt_pk_bf16_f32 v23, v18, v19
	global_store_dwordx4 v144, v[20:23], s[10:11] offset:256
	s_waitcnt vmcnt(15)
	v_lshlrev_b32_e32 v178, 16, v198
	v_and_b32_e32 v179, 0xffff0000, v198
	v_lshlrev_b32_e32 v180, 16, v199
	v_and_b32_e32 v181, 0xffff0000, v199
	v_lshlrev_b32_e32 v182, 16, v200
	v_and_b32_e32 v183, 0xffff0000, v200
	v_lshlrev_b32_e32 v184, 16, v201
	v_and_b32_e32 v185, 0xffff0000, v201
	v_pk_fma_f32 v[12:13], v[12:13], v[100:101], v[178:179]
	v_pk_fma_f32 v[14:15], v[14:15], v[102:103], v[180:181]
	v_pk_fma_f32 v[8:9], v[8:9], v[96:97], v[182:183]
	v_pk_fma_f32 v[10:11], v[10:11], v[98:99], v[184:185]
	s_add_u32 s10, s10, 0x8000
	s_addc_u32 s11, s11, 0
	v_cvt_pk_bf16_f32 v12, v12, v13
	v_cvt_pk_bf16_f32 v13, v14, v15
	v_cvt_pk_bf16_f32 v14, v8, v9
	v_cvt_pk_bf16_f32 v15, v10, v11
	global_store_dwordx4 v144, v[12:15], s[10:11]
	s_waitcnt vmcnt(14)
	v_lshlrev_b32_e32 v178, 16, v202
	v_and_b32_e32 v179, 0xffff0000, v202
	v_lshlrev_b32_e32 v180, 16, v203
	v_and_b32_e32 v181, 0xffff0000, v203
	v_lshlrev_b32_e32 v182, 16, v204
	v_and_b32_e32 v183, 0xffff0000, v204
	v_lshlrev_b32_e32 v184, 16, v205
	v_and_b32_e32 v185, 0xffff0000, v205
	v_pk_fma_f32 v[4:5], v[4:5], v[88:89], v[178:179]
	v_pk_fma_f32 v[6:7], v[6:7], v[90:91], v[180:181]
	v_pk_fma_f32 v[0:1], v[0:1], v[80:81], v[182:183]
	v_pk_fma_f32 v[2:3], v[2:3], v[82:83], v[184:185]
	v_cvt_pk_bf16_f32 v4, v4, v5
	v_cvt_pk_bf16_f32 v5, v6, v7
	v_cvt_pk_bf16_f32 v6, v0, v1
	v_cvt_pk_bf16_f32 v7, v2, v3
	global_store_dwordx4 v144, v[4:7], s[10:11] offset:256
	s_branch .LBB0_1047
